# MLA staggered waves 4-7: barrier moved behind the 2nd PV MFMA (3-slot ring)
# speedup vs baseline: 1.0048x; 1.0048x over previous
; __device__ __forceinline__ void finishSM9(f32x16& p0, f32x16& p1, float alpha, float& l_reg, v8i32& p8) {
; #pragma unroll
;   for (int r = 0; r < 16; ++r) { p0[r] = __builtin_amdgcn_exp2f(p0[r]); p1[r] = __builtin_amdgcn_exp2f(p1[r]); }
;   float ps = 0;
; #pragma unroll
;   for (int r = 0; r < 16; ++r) ps += p0[r];
; #pragma unroll
;   for (int r = 0; r < 16; ++r) ps += p1[r];
;   { auto rr = __builtin_amdgcn_permlane32_swap(__float_as_uint(ps), __float_as_uint(ps), false, false);
;     ps = __uint_as_float(rr[0]) + __uint_as_float(rr[1]); }
;   l_reg = l_reg * alpha + ps;
; #pragma unroll
;   for (int g = 0; g < 4; ++g) {
;     int w = __builtin_amdgcn_cvt_pk_fp8_f32(p0[4 * g], p0[4 * g + 1], 0, false); p8[g] = __builtin_amdgcn_cvt_pk_fp8_f32(p0[4 * g + 2], p0[4 * g + 3], w, true);
;     int u = __builtin_amdgcn_cvt_pk_fp8_f32(p1[4 * g], p1[4 * g + 1], 0, false); p8[4 + g] = __builtin_amdgcn_cvt_pk_fp8_f32(p1[4 * g + 2], p1[4 * g + 3], u, true); }
; }
; __device__ __forceinline__ void pv8(f32x16* o, const char* Vt, const v8i32 p8, int r32, int hi) {
;   const int sw = (r32 >> 2) & 3, a0 = r32 * 64 + (((hi * 2) ^ sw) << 4), a1 = r32 * 64 + (((hi * 2 + 1) ^ sw) << 4);
; #pragma unroll
;   for (int d0 = 0; d0 < 4; ++d0) {
;     const v8i32 vf = cat8(*reinterpret_cast<const v4i32*>(Vt + d0 * 2048 + a0), *reinterpret_cast<const v4i32*>(Vt + d0 * 2048 + a1));
;     o[d0] = __builtin_amdgcn_mfma_scale_f32_32x32x64_f8f6f4(p8, vf, o[d0], 0, 0, 0, 127, 0, 127); }
; }
; __device__ __forceinline__ void attn_unit7(const unsigned char* __restrict__ Q8, int ldq, const unsigned char* __restrict__ Kn8, int ldk, const unsigned char* __restrict__ Kr8, ...
;     ...
;   for (int j = 1; j + 1 < NT; j += 2) {
;     SLOAD();
;     qkt9(pB0, pB1, Kn_lds + 8192, Kr_lds + 4096, qf, 7.0f - m_reg, r32, hi);
;     finishSM9(pA0, pA1, alA, l_reg, p8);
;     pv8(o, Vt_lds, p8, r32, hi); partialSM9(pB0, pB1, m_reg, alB, thr_raw);
;     __syncthreads(); SWRITE(0);
;     RESC(alB); __syncthreads();
;     if (j + 2 < NT) SLOAD();
;     qkt9(pA0, pA1, Kn_lds, Kr_lds, qf, 7.0f - m_reg, r32, hi);
;     finishSM9(pB0, pB1, alB, l_reg, p8);
;     pv8(o, Vt_lds + 8192, p8, r32, hi); partialSM9(pA0, pA1, m_reg, alA, thr_raw);
;     __syncthreads(); if (j + 2 < NT) SWRITE(1);
;     RESC(alA); __syncthreads();
.Lmla_stag_loop:
	ds_read_b128 v[114:117], v215 offset:24576
	ds_read_b128 v[118:121], v216 offset:24576
	ds_read_b128 v[222:225], v215 offset:28672
	ds_read_b128 v[226:229], v216 offset:28672
	v_exp_f32_e32 v0, v82
	v_exp_f32_e32 v177, v83
	v_exp_f32_e32 v179, v84
	v_exp_f32_e32 v254, v85
	v_add_f32_e32 v219, v0, v177
	v_cvt_pk_fp8_f32 v246, v0, v177
	v_add_f32_e32 v219, v179, v219
	v_add_f32_e32 v219, v254, v219
	v_cvt_pk_fp8_f32 v246, v179, v254 op_sel:[0,0,1]
	s_waitcnt lgkmcnt(2)
	v_mfma_scale_f32_32x32x64_f8f6f4 v[114:129], v[114:121], v[146:153], v[230:245], v194, v193 op_sel_hi:[0,0,0]
	v_exp_f32_e32 v0, v86
	v_exp_f32_e32 v177, v87
	v_exp_f32_e32 v179, v88
	v_exp_f32_e32 v254, v89
	v_add_f32_e32 v219, v0, v219
	v_add_f32_e32 v219, v177, v219
	v_cvt_pk_fp8_f32 v247, v0, v177
	v_add_f32_e32 v219, v179, v219
	v_add_f32_e32 v219, v254, v219
	v_cvt_pk_fp8_f32 v247, v179, v254 op_sel:[0,0,1]
	ds_read_b128 v[82:85], v213 offset:24576
	ds_read_b128 v[86:89], v214 offset:24576
	s_waitcnt lgkmcnt(2)
	v_mfma_scale_f32_32x32x64_f8f6f4 v[98:113], v[222:229], v[146:153], v[230:245], v194, v193 op_sel_hi:[0,0,0]
	ds_read_b128 v[222:225], v213 offset:28672
	ds_read_b128 v[226:229], v214 offset:28672
	v_exp_f32_e32 v0, v90
	v_exp_f32_e32 v177, v91
	v_exp_f32_e32 v179, v92
	v_exp_f32_e32 v254, v93
	v_add_f32_e32 v219, v0, v219
	v_add_f32_e32 v219, v177, v219
	v_cvt_pk_fp8_f32 v248, v0, v177
	v_add_f32_e32 v219, v179, v219
	v_add_f32_e32 v219, v254, v219
	v_cvt_pk_fp8_f32 v248, v179, v254 op_sel:[0,0,1]
	v_exp_f32_e32 v0, v94
	v_exp_f32_e32 v177, v95
	v_exp_f32_e32 v179, v96
	v_exp_f32_e32 v254, v97
	v_add_f32_e32 v219, v0, v219
	v_add_f32_e32 v219, v177, v219
	v_cvt_pk_fp8_f32 v249, v0, v177
	v_add_f32_e32 v219, v179, v219
	v_add_f32_e32 v219, v254, v219
	v_cvt_pk_fp8_f32 v249, v179, v254 op_sel:[0,0,1]
	ds_read_b128 v[90:93], v185 offset:36864
	ds_read_b128 v[94:97], v186 offset:36864
	s_waitcnt lgkmcnt(4)
	v_mfma_scale_f32_32x32x64_f8f6f4 v[114:129], v[82:89], v[138:145], v[114:129], v194, v193 op_sel_hi:[0,0,0]
	v_exp_f32_e32 v0, v66
	v_exp_f32_e32 v177, v67
	v_exp_f32_e32 v179, v68
	v_exp_f32_e32 v254, v69
	v_add_f32_e32 v219, v0, v219
	v_add_f32_e32 v219, v177, v219
	v_cvt_pk_fp8_f32 v250, v0, v177
	v_add_f32_e32 v219, v179, v219
	v_add_f32_e32 v219, v254, v219
	v_cvt_pk_fp8_f32 v250, v179, v254 op_sel:[0,0,1]
	s_waitcnt lgkmcnt(2)
	v_mfma_scale_f32_32x32x64_f8f6f4 v[98:113], v[222:229], v[138:145], v[98:113], v194, v193 op_sel_hi:[0,0,0]
	ds_read_b128 v[222:225], v185 offset:38912
	ds_read_b128 v[226:229], v186 offset:38912
	v_exp_f32_e32 v0, v70
	v_exp_f32_e32 v177, v71
	v_exp_f32_e32 v179, v72
	v_exp_f32_e32 v254, v73
	v_add_f32_e32 v219, v0, v219
	v_add_f32_e32 v219, v177, v219
	v_cvt_pk_fp8_f32 v251, v0, v177
	v_add_f32_e32 v219, v179, v219
	v_add_f32_e32 v219, v254, v219
	v_cvt_pk_fp8_f32 v251, v179, v254 op_sel:[0,0,1]
	v_exp_f32_e32 v0, v74
	v_exp_f32_e32 v177, v75
	v_exp_f32_e32 v179, v76
	v_exp_f32_e32 v254, v77
	v_add_f32_e32 v219, v0, v219
	v_add_f32_e32 v219, v177, v219
	v_cvt_pk_fp8_f32 v252, v0, v177
	v_add_f32_e32 v219, v179, v219
	v_add_f32_e32 v219, v254, v219
	v_cvt_pk_fp8_f32 v252, v179, v254 op_sel:[0,0,1]
	s_waitcnt lgkmcnt(2)
	v_mfma_scale_f32_32x32x64_f8f6f4 v[114:129], v[90:97], v[130:137], v[114:129], v194, v193 op_sel_hi:[0,0,0]
	v_exp_f32_e32 v0, v78
	v_exp_f32_e32 v177, v79
	v_exp_f32_e32 v179, v80
	v_exp_f32_e32 v254, v81
	v_add_f32_e32 v219, v0, v219
	v_add_f32_e32 v219, v177, v219
	v_cvt_pk_fp8_f32 v253, v0, v177
	v_add_f32_e32 v219, v179, v219
	v_add_f32_e32 v219, v254, v219
	v_cvt_pk_fp8_f32 v253, v179, v254 op_sel:[0,0,1]
	ds_read_b128 v[90:93], v185 offset:0
	ds_read_b128 v[94:97], v186 offset:0
	ds_read_b128 v[82:85], v185 offset:2048
	ds_read_b128 v[86:89], v186 offset:2048
	ds_read_b128 v[74:77], v185 offset:4096
	ds_read_b128 v[78:81], v186 offset:4096
	ds_read_b128 v[66:69], v185 offset:6144
	ds_read_b128 v[70:73], v186 offset:6144
	s_waitcnt lgkmcnt(8)
	v_mfma_scale_f32_32x32x64_f8f6f4 v[98:113], v[222:229], v[130:137], v[98:113], v194, v193 op_sel_hi:[0,0,0]
	v_mov_b32_e32 v0, v219
	s_nop 1
	v_permlane32_swap_b32_e32 v219, v0
	v_add_f32_e32 v219, v219, v0
	v_fma_f32 v209, v209, v218, v219
	v_max_f32_e32 v177, v114, v115
	v_max3_f32 v177, v177, v116, v117
	v_max3_f32 v177, v177, v118, v119
	v_max3_f32 v177, v177, v120, v121
	v_max3_f32 v177, v177, v122, v123
	v_max3_f32 v177, v177, v124, v125
	v_max3_f32 v177, v177, v126, v127
	v_max3_f32 v177, v177, v128, v129
	s_waitcnt lgkmcnt(6)
	v_mfma_scale_f32_32x32x64_f8f6f4 v[50:65], v[246:253], v[90:97], v[50:65], v194, v194 op_sel_hi:[0,0,0]
	s_waitcnt lgkmcnt(4)
	v_mfma_scale_f32_32x32x64_f8f6f4 v[34:49], v[246:253], v[82:89], v[34:49], v194, v194 op_sel_hi:[0,0,0]
	s_waitcnt vmcnt(0)
	ds_write_b128 v210, v[158:161] offset:43008
	ds_write_b128 v211, v[162:165] offset:51200
	s_waitcnt lgkmcnt(0)
	s_barrier
	global_load_dwordx4 v[158:161], v176, s[18:19]
	global_load_dwordx4 v[162:165], v178, s[16:17]
	v_add_u32_e32 v176, 0x2000, v176
	v_add_u32_e32 v178, 0x20000, v178
	s_waitcnt lgkmcnt(2)
	v_mfma_scale_f32_32x32x64_f8f6f4 v[18:33], v[246:253], v[74:81], v[18:33], v194, v194 op_sel_hi:[0,0,0]
	s_waitcnt lgkmcnt(0)
	v_mfma_scale_f32_32x32x64_f8f6f4 v[2:17], v[246:253], v[66:73], v[2:17], v194, v194 op_sel_hi:[0,0,0]
	v_max_f32_e32 v0, v98, v99
	v_max3_f32 v0, v0, v100, v101
	v_max3_f32 v0, v0, v102, v103
	v_max3_f32 v0, v0, v104, v105
	v_max3_f32 v0, v0, v106, v107
	v_max3_f32 v0, v0, v108, v109
	v_max3_f32 v0, v0, v110, v111
	v_max3_f32 v0, v0, v112, v113
	v_max_f32_e32 v177, v177, v0
	v_mov_b32_e32 v0, v177
	v_mov_b32_e32 v221, 1.0
	s_nop 0
	v_permlane32_swap_b32_e32 v177, v0
	v_max_f32_e32 v177, v177, v0
	v_cmp_ge_f32_e32 vcc, s90, v177
	s_cmp_eq_u64 vcc, exec
	s_cbranch_scc0 .Lmla_s0_newmax
; __device__ __forceinline__ void finishSM9(f32x16& p0, f32x16& p1, float alpha, float& l_reg, v8i32& p8) {
; #pragma unroll
;   for (int r = 0; r < 16; ++r) { p0[r] = __builtin_amdgcn_exp2f(p0[r]); p1[r] = __builtin_amdgcn_exp2f(p1[r]); }
;   float ps = 0;
; #pragma unroll
;   for (int r = 0; r < 16; ++r) ps += p0[r];
; #pragma unroll
;   for (int r = 0; r < 16; ++r) ps += p1[r];
;   { auto rr = __builtin_amdgcn_permlane32_swap(__float_as_uint(ps), __float_as_uint(ps), false, false);
;     ps = __uint_as_float(rr[0]) + __uint_as_float(rr[1]); }
;   l_reg = l_reg * alpha + ps;
; #pragma unroll
;   for (int g = 0; g < 4; ++g) {
;     int w = __builtin_amdgcn_cvt_pk_fp8_f32(p0[4 * g], p0[4 * g + 1], 0, false); p8[g] = __builtin_amdgcn_cvt_pk_fp8_f32(p0[4 * g + 2], p0[4 * g + 3], w, true);
;     int u = __builtin_amdgcn_cvt_pk_fp8_f32(p1[4 * g], p1[4 * g + 1], 0, false); p8[4 + g] = __builtin_amdgcn_cvt_pk_fp8_f32(p1[4 * g + 2], p1[4 * g + 3], u, true); }
; }
; __device__ __forceinline__ void pv8(f32x16* o, const char* Vt, const v8i32 p8, int r32, int hi) {
;   const int sw = (r32 >> 2) & 3, a0 = r32 * 64 + (((hi * 2) ^ sw) << 4), a1 = r32 * 64 + (((hi * 2 + 1) ^ sw) << 4);
; #pragma unroll
;   for (int d0 = 0; d0 < 4; ++d0) {
;     const v8i32 vf = cat8(*reinterpret_cast<const v4i32*>(Vt + d0 * 2048 + a0), *reinterpret_cast<const v4i32*>(Vt + d0 * 2048 + a1));
;     o[d0] = __builtin_amdgcn_mfma_scale_f32_32x32x64_f8f6f4(p8, vf, o[d0], 0, 0, 0, 127, 0, 127); }
; }
; __device__ __forceinline__ void attn_unit7(const unsigned char* __restrict__ Q8, int ldq, const unsigned char* __restrict__ Kn8, int ldk, const unsigned char* __restrict__ Kr8, ...
;     ...
;   for (int j = 1; j + 1 < NT; j += 2) {
;     SLOAD();
;     qkt9(pB0, pB1, Kn_lds + 8192, Kr_lds + 4096, qf, 7.0f - m_reg, r32, hi);
;     finishSM9(pA0, pA1, alA, l_reg, p8);
;     pv8(o, Vt_lds, p8, r32, hi); partialSM9(pB0, pB1, m_reg, alB, thr_raw);
;     __syncthreads(); SWRITE(0);
;     RESC(alB); __syncthreads();
;     if (j + 2 < NT) SLOAD();
;     qkt9(pA0, pA1, Kn_lds, Kr_lds, qf, 7.0f - m_reg, r32, hi);
;     finishSM9(pB0, pB1, alB, l_reg, p8);
;     pv8(o, Vt_lds + 8192, p8, r32, hi); partialSM9(pA0, pA1, m_reg, alA, thr_raw);
;     __syncthreads(); if (j + 2 < NT) SWRITE(1);
;     RESC(alA); __syncthreads();
.Lmla_s0_cont:
	ds_read_b128 v[82:85], v215 offset:51200
	ds_read_b128 v[86:89], v216 offset:51200
	ds_read_b128 v[222:225], v215 offset:55296
	ds_read_b128 v[226:229], v216 offset:55296
	v_exp_f32_e32 v0, v114
	v_exp_f32_e32 v177, v115
	v_exp_f32_e32 v179, v116
	v_exp_f32_e32 v254, v117
	v_add_f32_e32 v219, v0, v177
	v_cvt_pk_fp8_f32 v246, v0, v177
	v_add_f32_e32 v219, v179, v219
	v_add_f32_e32 v219, v254, v219
	v_cvt_pk_fp8_f32 v246, v179, v254 op_sel:[0,0,1]
	s_waitcnt lgkmcnt(2)
	v_mfma_scale_f32_32x32x64_f8f6f4 v[82:97], v[82:89], v[146:153], v[230:245], v194, v193 op_sel_hi:[0,0,0]
	v_exp_f32_e32 v0, v118
	v_exp_f32_e32 v177, v119
	v_exp_f32_e32 v179, v120
	v_exp_f32_e32 v254, v121
	v_add_f32_e32 v219, v0, v219
	v_add_f32_e32 v219, v177, v219
	v_cvt_pk_fp8_f32 v247, v0, v177
	v_add_f32_e32 v219, v179, v219
	v_add_f32_e32 v219, v254, v219
	v_cvt_pk_fp8_f32 v247, v179, v254 op_sel:[0,0,1]
	ds_read_b128 v[114:117], v213 offset:51200
	ds_read_b128 v[118:121], v214 offset:51200
	s_waitcnt lgkmcnt(2)
	v_mfma_scale_f32_32x32x64_f8f6f4 v[66:81], v[222:229], v[146:153], v[230:245], v194, v193 op_sel_hi:[0,0,0]
	ds_read_b128 v[222:225], v213 offset:55296
	ds_read_b128 v[226:229], v214 offset:55296
	v_exp_f32_e32 v0, v122
	v_exp_f32_e32 v177, v123
	v_exp_f32_e32 v179, v124
	v_exp_f32_e32 v254, v125
	v_add_f32_e32 v219, v0, v219
	v_add_f32_e32 v219, v177, v219
	v_cvt_pk_fp8_f32 v248, v0, v177
	v_add_f32_e32 v219, v179, v219
	v_add_f32_e32 v219, v254, v219
	v_cvt_pk_fp8_f32 v248, v179, v254 op_sel:[0,0,1]
	v_exp_f32_e32 v0, v126
	v_exp_f32_e32 v177, v127
	v_exp_f32_e32 v179, v128
	v_exp_f32_e32 v254, v129
	v_add_f32_e32 v219, v0, v219
	v_add_f32_e32 v219, v177, v219
	v_cvt_pk_fp8_f32 v249, v0, v177
	v_add_f32_e32 v219, v179, v219
	v_add_f32_e32 v219, v254, v219
	v_cvt_pk_fp8_f32 v249, v179, v254 op_sel:[0,0,1]
	ds_read_b128 v[122:125], v185 offset:59392
	ds_read_b128 v[126:129], v186 offset:59392
	s_waitcnt lgkmcnt(4)
	v_mfma_scale_f32_32x32x64_f8f6f4 v[82:97], v[114:121], v[138:145], v[82:97], v194, v193 op_sel_hi:[0,0,0]
	v_exp_f32_e32 v0, v98
	v_exp_f32_e32 v177, v99
	v_exp_f32_e32 v179, v100
	v_exp_f32_e32 v254, v101
	v_add_f32_e32 v219, v0, v219
	v_add_f32_e32 v219, v177, v219
	v_cvt_pk_fp8_f32 v250, v0, v177
	v_add_f32_e32 v219, v179, v219
	v_add_f32_e32 v219, v254, v219
	v_cvt_pk_fp8_f32 v250, v179, v254 op_sel:[0,0,1]
	s_waitcnt lgkmcnt(2)
	v_mfma_scale_f32_32x32x64_f8f6f4 v[66:81], v[222:229], v[138:145], v[66:81], v194, v193 op_sel_hi:[0,0,0]
	ds_read_b128 v[222:225], v185 offset:61440
	ds_read_b128 v[226:229], v186 offset:61440
	v_exp_f32_e32 v0, v102
	v_exp_f32_e32 v177, v103
	v_exp_f32_e32 v179, v104
	v_exp_f32_e32 v254, v105
	v_add_f32_e32 v219, v0, v219
	v_add_f32_e32 v219, v177, v219
	v_cvt_pk_fp8_f32 v251, v0, v177
	v_add_f32_e32 v219, v179, v219
	v_add_f32_e32 v219, v254, v219
	v_cvt_pk_fp8_f32 v251, v179, v254 op_sel:[0,0,1]
	v_exp_f32_e32 v0, v106
	v_exp_f32_e32 v177, v107
	v_exp_f32_e32 v179, v108
	v_exp_f32_e32 v254, v109
	v_add_f32_e32 v219, v0, v219
	v_add_f32_e32 v219, v177, v219
	v_cvt_pk_fp8_f32 v252, v0, v177
	v_add_f32_e32 v219, v179, v219
	v_add_f32_e32 v219, v254, v219
	v_cvt_pk_fp8_f32 v252, v179, v254 op_sel:[0,0,1]
	s_waitcnt lgkmcnt(2)
	v_mfma_scale_f32_32x32x64_f8f6f4 v[82:97], v[122:129], v[130:137], v[82:97], v194, v193 op_sel_hi:[0,0,0]
	v_exp_f32_e32 v0, v110
	v_exp_f32_e32 v177, v111
	v_exp_f32_e32 v179, v112
	v_exp_f32_e32 v254, v113
	v_add_f32_e32 v219, v0, v219
	v_add_f32_e32 v219, v177, v219
	v_cvt_pk_fp8_f32 v253, v0, v177
	v_add_f32_e32 v219, v179, v219
	v_add_f32_e32 v219, v254, v219
	v_cvt_pk_fp8_f32 v253, v179, v254 op_sel:[0,0,1]
	ds_read_b128 v[122:125], v185 offset:8192
	ds_read_b128 v[126:129], v186 offset:8192
	ds_read_b128 v[114:117], v185 offset:10240
	ds_read_b128 v[118:121], v186 offset:10240
	ds_read_b128 v[106:109], v185 offset:12288
	ds_read_b128 v[110:113], v186 offset:12288
	ds_read_b128 v[98:101], v185 offset:14336
	ds_read_b128 v[102:105], v186 offset:14336
	s_waitcnt lgkmcnt(8)
	v_mfma_scale_f32_32x32x64_f8f6f4 v[66:81], v[222:229], v[130:137], v[66:81], v194, v193 op_sel_hi:[0,0,0]
	v_mov_b32_e32 v0, v219
	s_nop 1
	v_permlane32_swap_b32_e32 v219, v0
	v_add_f32_e32 v219, v219, v0
	v_fma_f32 v209, v209, v221, v219
	v_max_f32_e32 v177, v82, v83
	v_max3_f32 v177, v177, v84, v85
	v_max3_f32 v177, v177, v86, v87
	v_max3_f32 v177, v177, v88, v89
	v_max3_f32 v177, v177, v90, v91
	v_max3_f32 v177, v177, v92, v93
	v_max3_f32 v177, v177, v94, v95
	v_max3_f32 v177, v177, v96, v97
	s_waitcnt lgkmcnt(6)
	v_mfma_scale_f32_32x32x64_f8f6f4 v[50:65], v[246:253], v[122:129], v[50:65], v194, v194 op_sel_hi:[0,0,0]
	s_waitcnt lgkmcnt(4)
	v_mfma_scale_f32_32x32x64_f8f6f4 v[34:49], v[246:253], v[114:121], v[34:49], v194, v194 op_sel_hi:[0,0,0]
	s_waitcnt vmcnt(0)
	ds_write_b128 v210, v[158:161]
	ds_write_b128 v211, v[162:165] offset:16384
	s_waitcnt lgkmcnt(0)
	s_barrier
	global_load_dwordx4 v[158:161], v176, s[18:19]
	global_load_dwordx4 v[162:165], v178, s[16:17]
	v_add_u32_e32 v176, 0x2000, v176
	v_add_u32_e32 v178, 0x20000, v178
	s_waitcnt lgkmcnt(2)
	v_mfma_scale_f32_32x32x64_f8f6f4 v[18:33], v[246:253], v[106:113], v[18:33], v194, v194 op_sel_hi:[0,0,0]
	s_waitcnt lgkmcnt(0)
	v_mfma_scale_f32_32x32x64_f8f6f4 v[2:17], v[246:253], v[98:105], v[2:17], v194, v194 op_sel_hi:[0,0,0]
	v_max_f32_e32 v0, v66, v67
	v_max3_f32 v0, v0, v68, v69
	v_max3_f32 v0, v0, v70, v71
	v_max3_f32 v0, v0, v72, v73
	v_max3_f32 v0, v0, v74, v75
	v_max3_f32 v0, v0, v76, v77
	v_max3_f32 v0, v0, v78, v79
	v_max3_f32 v0, v0, v80, v81
	v_max_f32_e32 v177, v177, v0
	v_mov_b32_e32 v0, v177
	v_mov_b32_e32 v218, 1.0
	s_nop 0
	v_permlane32_swap_b32_e32 v177, v0
	v_max_f32_e32 v177, v177, v0
	v_cmp_ge_f32_e32 vcc, s90, v177
	s_cmp_eq_u64 vcc, exec
	s_cbranch_scc0 .Lmla_s1_newmax
; __device__ __forceinline__ void finishSM9(f32x16& p0, f32x16& p1, float alpha, float& l_reg, v8i32& p8) {
; #pragma unroll
;   for (int r = 0; r < 16; ++r) { p0[r] = __builtin_amdgcn_exp2f(p0[r]); p1[r] = __builtin_amdgcn_exp2f(p1[r]); }
;   float ps = 0;
; #pragma unroll
;   for (int r = 0; r < 16; ++r) ps += p0[r];
; #pragma unroll
;   for (int r = 0; r < 16; ++r) ps += p1[r];
;   { auto rr = __builtin_amdgcn_permlane32_swap(__float_as_uint(ps), __float_as_uint(ps), false, false);
;     ps = __uint_as_float(rr[0]) + __uint_as_float(rr[1]); }
;   l_reg = l_reg * alpha + ps;
; #pragma unroll
;   for (int g = 0; g < 4; ++g) {
;     int w = __builtin_amdgcn_cvt_pk_fp8_f32(p0[4 * g], p0[4 * g + 1], 0, false); p8[g] = __builtin_amdgcn_cvt_pk_fp8_f32(p0[4 * g + 2], p0[4 * g + 3], w, true);
;     int u = __builtin_amdgcn_cvt_pk_fp8_f32(p1[4 * g], p1[4 * g + 1], 0, false); p8[4 + g] = __builtin_amdgcn_cvt_pk_fp8_f32(p1[4 * g + 2], p1[4 * g + 3], u, true); }
; }
; __device__ __forceinline__ void pv8(f32x16* o, const char* Vt, const v8i32 p8, int r32, int hi) {
;   const int sw = (r32 >> 2) & 3, a0 = r32 * 64 + (((hi * 2) ^ sw) << 4), a1 = r32 * 64 + (((hi * 2 + 1) ^ sw) << 4);
; #pragma unroll
;   for (int d0 = 0; d0 < 4; ++d0) {
;     const v8i32 vf = cat8(*reinterpret_cast<const v4i32*>(Vt + d0 * 2048 + a0), *reinterpret_cast<const v4i32*>(Vt + d0 * 2048 + a1));
;     o[d0] = __builtin_amdgcn_mfma_scale_f32_32x32x64_f8f6f4(p8, vf, o[d0], 0, 0, 0, 127, 0, 127); }
; }
; __device__ __forceinline__ void attn_unit7(const unsigned char* __restrict__ Q8, int ldq, const unsigned char* __restrict__ Kn8, int ldk, const unsigned char* __restrict__ Kr8, ...
;     ...
;   for (int j = 1; j + 1 < NT; j += 2) {
;     SLOAD();
;     qkt9(pB0, pB1, Kn_lds + 8192, Kr_lds + 4096, qf, 7.0f - m_reg, r32, hi);
;     finishSM9(pA0, pA1, alA, l_reg, p8);
;     pv8(o, Vt_lds, p8, r32, hi); partialSM9(pB0, pB1, m_reg, alB, thr_raw);
;     __syncthreads(); SWRITE(0);
;     RESC(alB); __syncthreads();
;     if (j + 2 < NT) SLOAD();
;     qkt9(pA0, pA1, Kn_lds, Kr_lds, qf, 7.0f - m_reg, r32, hi);
;     finishSM9(pB0, pB1, alB, l_reg, p8);
;     pv8(o, Vt_lds + 8192, p8, r32, hi); partialSM9(pA0, pA1, m_reg, alA, thr_raw);
;     __syncthreads(); if (j + 2 < NT) SWRITE(1);
;     RESC(alA); __syncthreads();
.Lmla_s1_cont:
	ds_read_b128 v[114:117], v215 offset:16384
	ds_read_b128 v[118:121], v216 offset:16384
	ds_read_b128 v[222:225], v215 offset:20480
	ds_read_b128 v[226:229], v216 offset:20480
	v_exp_f32_e32 v0, v82
	v_exp_f32_e32 v177, v83
	v_exp_f32_e32 v179, v84
	v_exp_f32_e32 v254, v85
	v_add_f32_e32 v219, v0, v177
	v_cvt_pk_fp8_f32 v246, v0, v177
	v_add_f32_e32 v219, v179, v219
	v_add_f32_e32 v219, v254, v219
	v_cvt_pk_fp8_f32 v246, v179, v254 op_sel:[0,0,1]
	s_waitcnt lgkmcnt(2)
	v_mfma_scale_f32_32x32x64_f8f6f4 v[114:129], v[114:121], v[146:153], v[230:245], v194, v193 op_sel_hi:[0,0,0]
	v_exp_f32_e32 v0, v86
	v_exp_f32_e32 v177, v87
	v_exp_f32_e32 v179, v88
	v_exp_f32_e32 v254, v89
	v_add_f32_e32 v219, v0, v219
	v_add_f32_e32 v219, v177, v219
	v_cvt_pk_fp8_f32 v247, v0, v177
	v_add_f32_e32 v219, v179, v219
	v_add_f32_e32 v219, v254, v219
	v_cvt_pk_fp8_f32 v247, v179, v254 op_sel:[0,0,1]
	ds_read_b128 v[82:85], v213 offset:16384
	ds_read_b128 v[86:89], v214 offset:16384
	s_waitcnt lgkmcnt(2)
	v_mfma_scale_f32_32x32x64_f8f6f4 v[98:113], v[222:229], v[146:153], v[230:245], v194, v193 op_sel_hi:[0,0,0]
	ds_read_b128 v[222:225], v213 offset:20480
	ds_read_b128 v[226:229], v214 offset:20480
	v_exp_f32_e32 v0, v90
	v_exp_f32_e32 v177, v91
	v_exp_f32_e32 v179, v92
	v_exp_f32_e32 v254, v93
	v_add_f32_e32 v219, v0, v219
	v_add_f32_e32 v219, v177, v219
	v_cvt_pk_fp8_f32 v248, v0, v177
	v_add_f32_e32 v219, v179, v219
	v_add_f32_e32 v219, v254, v219
	v_cvt_pk_fp8_f32 v248, v179, v254 op_sel:[0,0,1]
	v_exp_f32_e32 v0, v94
	v_exp_f32_e32 v177, v95
	v_exp_f32_e32 v179, v96
	v_exp_f32_e32 v254, v97
	v_add_f32_e32 v219, v0, v219
	v_add_f32_e32 v219, v177, v219
	v_cvt_pk_fp8_f32 v249, v0, v177
	v_add_f32_e32 v219, v179, v219
	v_add_f32_e32 v219, v254, v219
	v_cvt_pk_fp8_f32 v249, v179, v254 op_sel:[0,0,1]
	ds_read_b128 v[90:93], v185 offset:32768
	ds_read_b128 v[94:97], v186 offset:32768
	s_waitcnt lgkmcnt(4)
	v_mfma_scale_f32_32x32x64_f8f6f4 v[114:129], v[82:89], v[138:145], v[114:129], v194, v193 op_sel_hi:[0,0,0]
	v_exp_f32_e32 v0, v66
	v_exp_f32_e32 v177, v67
	v_exp_f32_e32 v179, v68
	v_exp_f32_e32 v254, v69
	v_add_f32_e32 v219, v0, v219
	v_add_f32_e32 v219, v177, v219
	v_cvt_pk_fp8_f32 v250, v0, v177
	v_add_f32_e32 v219, v179, v219
	v_add_f32_e32 v219, v254, v219
	v_cvt_pk_fp8_f32 v250, v179, v254 op_sel:[0,0,1]
	s_waitcnt lgkmcnt(2)
	v_mfma_scale_f32_32x32x64_f8f6f4 v[98:113], v[222:229], v[138:145], v[98:113], v194, v193 op_sel_hi:[0,0,0]
	ds_read_b128 v[222:225], v185 offset:34816
	ds_read_b128 v[226:229], v186 offset:34816
	v_exp_f32_e32 v0, v70
	v_exp_f32_e32 v177, v71
	v_exp_f32_e32 v179, v72
	v_exp_f32_e32 v254, v73
	v_add_f32_e32 v219, v0, v219
	v_add_f32_e32 v219, v177, v219
	v_cvt_pk_fp8_f32 v251, v0, v177
	v_add_f32_e32 v219, v179, v219
	v_add_f32_e32 v219, v254, v219
	v_cvt_pk_fp8_f32 v251, v179, v254 op_sel:[0,0,1]
	v_exp_f32_e32 v0, v74
	v_exp_f32_e32 v177, v75
	v_exp_f32_e32 v179, v76
	v_exp_f32_e32 v254, v77
	v_add_f32_e32 v219, v0, v219
	v_add_f32_e32 v219, v177, v219
	v_cvt_pk_fp8_f32 v252, v0, v177
	v_add_f32_e32 v219, v179, v219
	v_add_f32_e32 v219, v254, v219
	v_cvt_pk_fp8_f32 v252, v179, v254 op_sel:[0,0,1]
	s_waitcnt lgkmcnt(2)
	v_mfma_scale_f32_32x32x64_f8f6f4 v[114:129], v[90:97], v[130:137], v[114:129], v194, v193 op_sel_hi:[0,0,0]
	v_exp_f32_e32 v0, v78
	v_exp_f32_e32 v177, v79
	v_exp_f32_e32 v179, v80
	v_exp_f32_e32 v254, v81
	v_add_f32_e32 v219, v0, v219
	v_add_f32_e32 v219, v177, v219
	v_cvt_pk_fp8_f32 v253, v0, v177
	v_add_f32_e32 v219, v179, v219
	v_add_f32_e32 v219, v254, v219
	v_cvt_pk_fp8_f32 v253, v179, v254 op_sel:[0,0,1]
	ds_read_b128 v[90:93], v185 offset:43008
	ds_read_b128 v[94:97], v186 offset:43008
	ds_read_b128 v[82:85], v185 offset:45056
	ds_read_b128 v[86:89], v186 offset:45056
	ds_read_b128 v[74:77], v185 offset:47104
	ds_read_b128 v[78:81], v186 offset:47104
	ds_read_b128 v[66:69], v185 offset:49152
	ds_read_b128 v[70:73], v186 offset:49152
	s_waitcnt lgkmcnt(8)
	v_mfma_scale_f32_32x32x64_f8f6f4 v[98:113], v[222:229], v[130:137], v[98:113], v194, v193 op_sel_hi:[0,0,0]
	v_mov_b32_e32 v0, v219
	s_nop 1
	v_permlane32_swap_b32_e32 v219, v0
	v_add_f32_e32 v219, v219, v0
	v_fma_f32 v209, v209, v218, v219
	v_max_f32_e32 v177, v114, v115
	v_max3_f32 v177, v177, v116, v117
	v_max3_f32 v177, v177, v118, v119
	v_max3_f32 v177, v177, v120, v121
	v_max3_f32 v177, v177, v122, v123
	v_max3_f32 v177, v177, v124, v125
	v_max3_f32 v177, v177, v126, v127
	v_max3_f32 v177, v177, v128, v129
	s_waitcnt lgkmcnt(6)
	v_mfma_scale_f32_32x32x64_f8f6f4 v[50:65], v[246:253], v[90:97], v[50:65], v194, v194 op_sel_hi:[0,0,0]
	s_waitcnt lgkmcnt(4)
	v_mfma_scale_f32_32x32x64_f8f6f4 v[34:49], v[246:253], v[82:89], v[34:49], v194, v194 op_sel_hi:[0,0,0]
	s_waitcnt vmcnt(0)
	ds_write_b128 v210, v[158:161] offset:8192
	ds_write_b128 v211, v[162:165] offset:24576
	s_waitcnt lgkmcnt(0)
	s_barrier
	global_load_dwordx4 v[158:161], v176, s[18:19]
	global_load_dwordx4 v[162:165], v178, s[16:17]
	v_add_u32_e32 v176, 0x2000, v176
	v_add_u32_e32 v178, 0x20000, v178
	s_waitcnt lgkmcnt(2)
	v_mfma_scale_f32_32x32x64_f8f6f4 v[18:33], v[246:253], v[74:81], v[18:33], v194, v194 op_sel_hi:[0,0,0]
	s_waitcnt lgkmcnt(0)
	v_mfma_scale_f32_32x32x64_f8f6f4 v[2:17], v[246:253], v[66:73], v[2:17], v194, v194 op_sel_hi:[0,0,0]
	v_max_f32_e32 v0, v98, v99
	v_max3_f32 v0, v0, v100, v101
	v_max3_f32 v0, v0, v102, v103
	v_max3_f32 v0, v0, v104, v105
	v_max3_f32 v0, v0, v106, v107
	v_max3_f32 v0, v0, v108, v109
	v_max3_f32 v0, v0, v110, v111
	v_max3_f32 v0, v0, v112, v113
	v_max_f32_e32 v177, v177, v0
	v_mov_b32_e32 v0, v177
	v_mov_b32_e32 v221, 1.0
	s_nop 0
	v_permlane32_swap_b32_e32 v177, v0
	v_max_f32_e32 v177, v177, v0
	v_cmp_ge_f32_e32 vcc, s90, v177
	s_cmp_eq_u64 vcc, exec
	s_cbranch_scc0 .Lmla_s2_newmax
; __device__ __forceinline__ void finishSM9(f32x16& p0, f32x16& p1, float alpha, float& l_reg, v8i32& p8) {
; #pragma unroll
;   for (int r = 0; r < 16; ++r) { p0[r] = __builtin_amdgcn_exp2f(p0[r]); p1[r] = __builtin_amdgcn_exp2f(p1[r]); }
;   float ps = 0;
; #pragma unroll
;   for (int r = 0; r < 16; ++r) ps += p0[r];
; #pragma unroll
;   for (int r = 0; r < 16; ++r) ps += p1[r];
;   { auto rr = __builtin_amdgcn_permlane32_swap(__float_as_uint(ps), __float_as_uint(ps), false, false);
;     ps = __uint_as_float(rr[0]) + __uint_as_float(rr[1]); }
;   l_reg = l_reg * alpha + ps;
; #pragma unroll
;   for (int g = 0; g < 4; ++g) {
;     int w = __builtin_amdgcn_cvt_pk_fp8_f32(p0[4 * g], p0[4 * g + 1], 0, false); p8[g] = __builtin_amdgcn_cvt_pk_fp8_f32(p0[4 * g + 2], p0[4 * g + 3], w, true);
;     int u = __builtin_amdgcn_cvt_pk_fp8_f32(p1[4 * g], p1[4 * g + 1], 0, false); p8[4 + g] = __builtin_amdgcn_cvt_pk_fp8_f32(p1[4 * g + 2], p1[4 * g + 3], u, true); }
; }
; __device__ __forceinline__ void pv8(f32x16* o, const char* Vt, const v8i32 p8, int r32, int hi) {
;   const int sw = (r32 >> 2) & 3, a0 = r32 * 64 + (((hi * 2) ^ sw) << 4), a1 = r32 * 64 + (((hi * 2 + 1) ^ sw) << 4);
; #pragma unroll
;   for (int d0 = 0; d0 < 4; ++d0) {
;     const v8i32 vf = cat8(*reinterpret_cast<const v4i32*>(Vt + d0 * 2048 + a0), *reinterpret_cast<const v4i32*>(Vt + d0 * 2048 + a1));
;     o[d0] = __builtin_amdgcn_mfma_scale_f32_32x32x64_f8f6f4(p8, vf, o[d0], 0, 0, 0, 127, 0, 127); }
; }
; __device__ __forceinline__ void attn_unit7(const unsigned char* __restrict__ Q8, int ldq, const unsigned char* __restrict__ Kn8, int ldk, const unsigned char* __restrict__ Kr8, ...
;     ...
;   for (int j = 1; j + 1 < NT; j += 2) {
;     SLOAD();
;     qkt9(pB0, pB1, Kn_lds + 8192, Kr_lds + 4096, qf, 7.0f - m_reg, r32, hi);
;     finishSM9(pA0, pA1, alA, l_reg, p8);
;     pv8(o, Vt_lds, p8, r32, hi); partialSM9(pB0, pB1, m_reg, alB, thr_raw);
;     __syncthreads(); SWRITE(0);
;     RESC(alB); __syncthreads();
;     if (j + 2 < NT) SLOAD();
;     qkt9(pA0, pA1, Kn_lds, Kr_lds, qf, 7.0f - m_reg, r32, hi);
;     finishSM9(pB0, pB1, alB, l_reg, p8);
;     pv8(o, Vt_lds + 8192, p8, r32, hi); partialSM9(pA0, pA1, m_reg, alA, thr_raw);
;     __syncthreads(); if (j + 2 < NT) SWRITE(1);
;     RESC(alA); __syncthreads();
.Lmla_s2_cont:
	ds_read_b128 v[82:85], v215 offset:24576
	ds_read_b128 v[86:89], v216 offset:24576
	ds_read_b128 v[222:225], v215 offset:28672
	ds_read_b128 v[226:229], v216 offset:28672
	v_exp_f32_e32 v0, v114
	v_exp_f32_e32 v177, v115
	v_exp_f32_e32 v179, v116
	v_exp_f32_e32 v254, v117
	v_add_f32_e32 v219, v0, v177
	v_cvt_pk_fp8_f32 v246, v0, v177
	v_add_f32_e32 v219, v179, v219
	v_add_f32_e32 v219, v254, v219
	v_cvt_pk_fp8_f32 v246, v179, v254 op_sel:[0,0,1]
	s_waitcnt lgkmcnt(2)
	v_mfma_scale_f32_32x32x64_f8f6f4 v[82:97], v[82:89], v[146:153], v[230:245], v194, v193 op_sel_hi:[0,0,0]
	v_exp_f32_e32 v0, v118
	v_exp_f32_e32 v177, v119
	v_exp_f32_e32 v179, v120
	v_exp_f32_e32 v254, v121
	v_add_f32_e32 v219, v0, v219
	v_add_f32_e32 v219, v177, v219
	v_cvt_pk_fp8_f32 v247, v0, v177
	v_add_f32_e32 v219, v179, v219
	v_add_f32_e32 v219, v254, v219
	v_cvt_pk_fp8_f32 v247, v179, v254 op_sel:[0,0,1]
	ds_read_b128 v[114:117], v213 offset:24576
	ds_read_b128 v[118:121], v214 offset:24576
	s_waitcnt lgkmcnt(2)
	v_mfma_scale_f32_32x32x64_f8f6f4 v[66:81], v[222:229], v[146:153], v[230:245], v194, v193 op_sel_hi:[0,0,0]
	ds_read_b128 v[222:225], v213 offset:28672
	ds_read_b128 v[226:229], v214 offset:28672
	v_exp_f32_e32 v0, v122
	v_exp_f32_e32 v177, v123
	v_exp_f32_e32 v179, v124
	v_exp_f32_e32 v254, v125
	v_add_f32_e32 v219, v0, v219
	v_add_f32_e32 v219, v177, v219
	v_cvt_pk_fp8_f32 v248, v0, v177
	v_add_f32_e32 v219, v179, v219
	v_add_f32_e32 v219, v254, v219
	v_cvt_pk_fp8_f32 v248, v179, v254 op_sel:[0,0,1]
	v_exp_f32_e32 v0, v126
	v_exp_f32_e32 v177, v127
	v_exp_f32_e32 v179, v128
	v_exp_f32_e32 v254, v129
	v_add_f32_e32 v219, v0, v219
	v_add_f32_e32 v219, v177, v219
	v_cvt_pk_fp8_f32 v249, v0, v177
	v_add_f32_e32 v219, v179, v219
	v_add_f32_e32 v219, v254, v219
	v_cvt_pk_fp8_f32 v249, v179, v254 op_sel:[0,0,1]
	ds_read_b128 v[122:125], v185 offset:36864
	ds_read_b128 v[126:129], v186 offset:36864
	s_waitcnt lgkmcnt(4)
	v_mfma_scale_f32_32x32x64_f8f6f4 v[82:97], v[114:121], v[138:145], v[82:97], v194, v193 op_sel_hi:[0,0,0]
	v_exp_f32_e32 v0, v98
	v_exp_f32_e32 v177, v99
	v_exp_f32_e32 v179, v100
	v_exp_f32_e32 v254, v101
	v_add_f32_e32 v219, v0, v219
	v_add_f32_e32 v219, v177, v219
	v_cvt_pk_fp8_f32 v250, v0, v177
	v_add_f32_e32 v219, v179, v219
	v_add_f32_e32 v219, v254, v219
	v_cvt_pk_fp8_f32 v250, v179, v254 op_sel:[0,0,1]
	s_waitcnt lgkmcnt(2)
	v_mfma_scale_f32_32x32x64_f8f6f4 v[66:81], v[222:229], v[138:145], v[66:81], v194, v193 op_sel_hi:[0,0,0]
	ds_read_b128 v[222:225], v185 offset:38912
	ds_read_b128 v[226:229], v186 offset:38912
	v_exp_f32_e32 v0, v102
	v_exp_f32_e32 v177, v103
	v_exp_f32_e32 v179, v104
	v_exp_f32_e32 v254, v105
	v_add_f32_e32 v219, v0, v219
	v_add_f32_e32 v219, v177, v219
	v_cvt_pk_fp8_f32 v251, v0, v177
	v_add_f32_e32 v219, v179, v219
	v_add_f32_e32 v219, v254, v219
	v_cvt_pk_fp8_f32 v251, v179, v254 op_sel:[0,0,1]
	v_exp_f32_e32 v0, v106
	v_exp_f32_e32 v177, v107
	v_exp_f32_e32 v179, v108
	v_exp_f32_e32 v254, v109
	v_add_f32_e32 v219, v0, v219
	v_add_f32_e32 v219, v177, v219
	v_cvt_pk_fp8_f32 v252, v0, v177
	v_add_f32_e32 v219, v179, v219
	v_add_f32_e32 v219, v254, v219
	v_cvt_pk_fp8_f32 v252, v179, v254 op_sel:[0,0,1]
	s_waitcnt lgkmcnt(2)
	v_mfma_scale_f32_32x32x64_f8f6f4 v[82:97], v[122:129], v[130:137], v[82:97], v194, v193 op_sel_hi:[0,0,0]
	v_exp_f32_e32 v0, v110
	v_exp_f32_e32 v177, v111
	v_exp_f32_e32 v179, v112
	v_exp_f32_e32 v254, v113
	v_add_f32_e32 v219, v0, v219
	v_add_f32_e32 v219, v177, v219
	v_cvt_pk_fp8_f32 v253, v0, v177
	v_add_f32_e32 v219, v179, v219
	v_add_f32_e32 v219, v254, v219
	v_cvt_pk_fp8_f32 v253, v179, v254 op_sel:[0,0,1]
	ds_read_b128 v[122:125], v185 offset:0
	ds_read_b128 v[126:129], v186 offset:0
	ds_read_b128 v[114:117], v185 offset:2048
	ds_read_b128 v[118:121], v186 offset:2048
	ds_read_b128 v[106:109], v185 offset:4096
	ds_read_b128 v[110:113], v186 offset:4096
	ds_read_b128 v[98:101], v185 offset:6144
	ds_read_b128 v[102:105], v186 offset:6144
	s_waitcnt lgkmcnt(8)
	v_mfma_scale_f32_32x32x64_f8f6f4 v[66:81], v[222:229], v[130:137], v[66:81], v194, v193 op_sel_hi:[0,0,0]
	v_mov_b32_e32 v0, v219
	s_nop 1
	v_permlane32_swap_b32_e32 v219, v0
	v_add_f32_e32 v219, v219, v0
	v_fma_f32 v209, v209, v221, v219
	v_max_f32_e32 v177, v82, v83
	v_max3_f32 v177, v177, v84, v85
	v_max3_f32 v177, v177, v86, v87
	v_max3_f32 v177, v177, v88, v89
	v_max3_f32 v177, v177, v90, v91
	v_max3_f32 v177, v177, v92, v93
	v_max3_f32 v177, v177, v94, v95
	v_max3_f32 v177, v177, v96, v97
	s_waitcnt lgkmcnt(6)
	v_mfma_scale_f32_32x32x64_f8f6f4 v[50:65], v[246:253], v[122:129], v[50:65], v194, v194 op_sel_hi:[0,0,0]
	s_waitcnt lgkmcnt(4)
	v_mfma_scale_f32_32x32x64_f8f6f4 v[34:49], v[246:253], v[114:121], v[34:49], v194, v194 op_sel_hi:[0,0,0]
	s_waitcnt vmcnt(0)
	ds_write_b128 v210, v[158:161] offset:43008
	ds_write_b128 v211, v[162:165] offset:51200
	s_waitcnt lgkmcnt(0)
	s_barrier
	global_load_dwordx4 v[158:161], v176, s[18:19]
	global_load_dwordx4 v[162:165], v178, s[16:17]
	v_add_u32_e32 v176, 0x2000, v176
	v_add_u32_e32 v178, 0x20000, v178
	s_waitcnt lgkmcnt(2)
	v_mfma_scale_f32_32x32x64_f8f6f4 v[18:33], v[246:253], v[106:113], v[18:33], v194, v194 op_sel_hi:[0,0,0]
	s_waitcnt lgkmcnt(0)
	v_mfma_scale_f32_32x32x64_f8f6f4 v[2:17], v[246:253], v[98:105], v[2:17], v194, v194 op_sel_hi:[0,0,0]
	v_max_f32_e32 v0, v66, v67
	v_max3_f32 v0, v0, v68, v69
	v_max3_f32 v0, v0, v70, v71
	v_max3_f32 v0, v0, v72, v73
	v_max3_f32 v0, v0, v74, v75
	v_max3_f32 v0, v0, v76, v77
	v_max3_f32 v0, v0, v78, v79
	v_max3_f32 v0, v0, v80, v81
	v_max_f32_e32 v177, v177, v0
	v_mov_b32_e32 v0, v177
	v_mov_b32_e32 v218, 1.0
	s_nop 0
	v_permlane32_swap_b32_e32 v177, v0
	v_max_f32_e32 v177, v177, v0
	v_cmp_ge_f32_e32 vcc, s90, v177
	s_cmp_eq_u64 vcc, exec
	s_cbranch_scc0 .Lmla_s3_newmax
; __device__ __forceinline__ void finishSM9(f32x16& p0, f32x16& p1, float alpha, float& l_reg, v8i32& p8) {
; #pragma unroll
;   for (int r = 0; r < 16; ++r) { p0[r] = __builtin_amdgcn_exp2f(p0[r]); p1[r] = __builtin_amdgcn_exp2f(p1[r]); }
;   float ps = 0;
; #pragma unroll
;   for (int r = 0; r < 16; ++r) ps += p0[r];
; #pragma unroll
;   for (int r = 0; r < 16; ++r) ps += p1[r];
;   { auto rr = __builtin_amdgcn_permlane32_swap(__float_as_uint(ps), __float_as_uint(ps), false, false);
;     ps = __uint_as_float(rr[0]) + __uint_as_float(rr[1]); }
;   l_reg = l_reg * alpha + ps;
; #pragma unroll
;   for (int g = 0; g < 4; ++g) {
;     int w = __builtin_amdgcn_cvt_pk_fp8_f32(p0[4 * g], p0[4 * g + 1], 0, false); p8[g] = __builtin_amdgcn_cvt_pk_fp8_f32(p0[4 * g + 2], p0[4 * g + 3], w, true);
;     int u = __builtin_amdgcn_cvt_pk_fp8_f32(p1[4 * g], p1[4 * g + 1], 0, false); p8[4 + g] = __builtin_amdgcn_cvt_pk_fp8_f32(p1[4 * g + 2], p1[4 * g + 3], u, true); }
; }
; __device__ __forceinline__ void pv8(f32x16* o, const char* Vt, const v8i32 p8, int r32, int hi) {
;   const int sw = (r32 >> 2) & 3, a0 = r32 * 64 + (((hi * 2) ^ sw) << 4), a1 = r32 * 64 + (((hi * 2 + 1) ^ sw) << 4);
; #pragma unroll
;   for (int d0 = 0; d0 < 4; ++d0) {
;     const v8i32 vf = cat8(*reinterpret_cast<const v4i32*>(Vt + d0 * 2048 + a0), *reinterpret_cast<const v4i32*>(Vt + d0 * 2048 + a1));
;     o[d0] = __builtin_amdgcn_mfma_scale_f32_32x32x64_f8f6f4(p8, vf, o[d0], 0, 0, 0, 127, 0, 127); }
; }
; __device__ __forceinline__ void attn_unit7(const unsigned char* __restrict__ Q8, int ldq, const unsigned char* __restrict__ Kn8, int ldk, const unsigned char* __restrict__ Kr8, ...
;     ...
;   for (int j = 1; j + 1 < NT; j += 2) {
;     SLOAD();
;     qkt9(pB0, pB1, Kn_lds + 8192, Kr_lds + 4096, qf, 7.0f - m_reg, r32, hi);
;     finishSM9(pA0, pA1, alA, l_reg, p8);
;     pv8(o, Vt_lds, p8, r32, hi); partialSM9(pB0, pB1, m_reg, alB, thr_raw);
;     __syncthreads(); SWRITE(0);
;     RESC(alB); __syncthreads();
;     if (j + 2 < NT) SLOAD();
;     qkt9(pA0, pA1, Kn_lds, Kr_lds, qf, 7.0f - m_reg, r32, hi);
;     finishSM9(pB0, pB1, alB, l_reg, p8);
;     pv8(o, Vt_lds + 8192, p8, r32, hi); partialSM9(pA0, pA1, m_reg, alA, thr_raw);
;     __syncthreads(); if (j + 2 < NT) SWRITE(1);
;     RESC(alA); __syncthreads();
.Lmla_s3_cont:
	ds_read_b128 v[114:117], v215 offset:51200
	ds_read_b128 v[118:121], v216 offset:51200
	ds_read_b128 v[222:225], v215 offset:55296
	ds_read_b128 v[226:229], v216 offset:55296
	v_exp_f32_e32 v0, v82
	v_exp_f32_e32 v177, v83
	v_exp_f32_e32 v179, v84
	v_exp_f32_e32 v254, v85
	v_add_f32_e32 v219, v0, v177
	v_cvt_pk_fp8_f32 v246, v0, v177
	v_add_f32_e32 v219, v179, v219
	v_add_f32_e32 v219, v254, v219
	v_cvt_pk_fp8_f32 v246, v179, v254 op_sel:[0,0,1]
	s_waitcnt lgkmcnt(2)
	v_mfma_scale_f32_32x32x64_f8f6f4 v[114:129], v[114:121], v[146:153], v[230:245], v194, v193 op_sel_hi:[0,0,0]
	v_exp_f32_e32 v0, v86
	v_exp_f32_e32 v177, v87
	v_exp_f32_e32 v179, v88
	v_exp_f32_e32 v254, v89
	v_add_f32_e32 v219, v0, v219
	v_add_f32_e32 v219, v177, v219
	v_cvt_pk_fp8_f32 v247, v0, v177
	v_add_f32_e32 v219, v179, v219
	v_add_f32_e32 v219, v254, v219
	v_cvt_pk_fp8_f32 v247, v179, v254 op_sel:[0,0,1]
	ds_read_b128 v[82:85], v213 offset:51200
	ds_read_b128 v[86:89], v214 offset:51200
	s_waitcnt lgkmcnt(2)
	v_mfma_scale_f32_32x32x64_f8f6f4 v[98:113], v[222:229], v[146:153], v[230:245], v194, v193 op_sel_hi:[0,0,0]
	ds_read_b128 v[222:225], v213 offset:55296
	ds_read_b128 v[226:229], v214 offset:55296
	v_exp_f32_e32 v0, v90
	v_exp_f32_e32 v177, v91
	v_exp_f32_e32 v179, v92
	v_exp_f32_e32 v254, v93
	v_add_f32_e32 v219, v0, v219
	v_add_f32_e32 v219, v177, v219
	v_cvt_pk_fp8_f32 v248, v0, v177
	v_add_f32_e32 v219, v179, v219
	v_add_f32_e32 v219, v254, v219
	v_cvt_pk_fp8_f32 v248, v179, v254 op_sel:[0,0,1]
	v_exp_f32_e32 v0, v94
	v_exp_f32_e32 v177, v95
	v_exp_f32_e32 v179, v96
	v_exp_f32_e32 v254, v97
	v_add_f32_e32 v219, v0, v219
	v_add_f32_e32 v219, v177, v219
	v_cvt_pk_fp8_f32 v249, v0, v177
	v_add_f32_e32 v219, v179, v219
	v_add_f32_e32 v219, v254, v219
	v_cvt_pk_fp8_f32 v249, v179, v254 op_sel:[0,0,1]
	ds_read_b128 v[90:93], v185 offset:59392
	ds_read_b128 v[94:97], v186 offset:59392
	s_waitcnt lgkmcnt(4)
	v_mfma_scale_f32_32x32x64_f8f6f4 v[114:129], v[82:89], v[138:145], v[114:129], v194, v193 op_sel_hi:[0,0,0]
	v_exp_f32_e32 v0, v66
	v_exp_f32_e32 v177, v67
	v_exp_f32_e32 v179, v68
	v_exp_f32_e32 v254, v69
	v_add_f32_e32 v219, v0, v219
	v_add_f32_e32 v219, v177, v219
	v_cvt_pk_fp8_f32 v250, v0, v177
	v_add_f32_e32 v219, v179, v219
	v_add_f32_e32 v219, v254, v219
	v_cvt_pk_fp8_f32 v250, v179, v254 op_sel:[0,0,1]
	s_waitcnt lgkmcnt(2)
	v_mfma_scale_f32_32x32x64_f8f6f4 v[98:113], v[222:229], v[138:145], v[98:113], v194, v193 op_sel_hi:[0,0,0]
	ds_read_b128 v[222:225], v185 offset:61440
	ds_read_b128 v[226:229], v186 offset:61440
	v_exp_f32_e32 v0, v70
	v_exp_f32_e32 v177, v71
	v_exp_f32_e32 v179, v72
	v_exp_f32_e32 v254, v73
	v_add_f32_e32 v219, v0, v219
	v_add_f32_e32 v219, v177, v219
	v_cvt_pk_fp8_f32 v251, v0, v177
	v_add_f32_e32 v219, v179, v219
	v_add_f32_e32 v219, v254, v219
	v_cvt_pk_fp8_f32 v251, v179, v254 op_sel:[0,0,1]
	v_exp_f32_e32 v0, v74
	v_exp_f32_e32 v177, v75
	v_exp_f32_e32 v179, v76
	v_exp_f32_e32 v254, v77
	v_add_f32_e32 v219, v0, v219
	v_add_f32_e32 v219, v177, v219
	v_cvt_pk_fp8_f32 v252, v0, v177
	v_add_f32_e32 v219, v179, v219
	v_add_f32_e32 v219, v254, v219
	v_cvt_pk_fp8_f32 v252, v179, v254 op_sel:[0,0,1]
	s_waitcnt lgkmcnt(2)
	v_mfma_scale_f32_32x32x64_f8f6f4 v[114:129], v[90:97], v[130:137], v[114:129], v194, v193 op_sel_hi:[0,0,0]
	v_exp_f32_e32 v0, v78
	v_exp_f32_e32 v177, v79
	v_exp_f32_e32 v179, v80
	v_exp_f32_e32 v254, v81
	v_add_f32_e32 v219, v0, v219
	v_add_f32_e32 v219, v177, v219
	v_cvt_pk_fp8_f32 v253, v0, v177
	v_add_f32_e32 v219, v179, v219
	v_add_f32_e32 v219, v254, v219
	v_cvt_pk_fp8_f32 v253, v179, v254 op_sel:[0,0,1]
	ds_read_b128 v[90:93], v185 offset:8192
	ds_read_b128 v[94:97], v186 offset:8192
	ds_read_b128 v[82:85], v185 offset:10240
	ds_read_b128 v[86:89], v186 offset:10240
	ds_read_b128 v[74:77], v185 offset:12288
	ds_read_b128 v[78:81], v186 offset:12288
	ds_read_b128 v[66:69], v185 offset:14336
	ds_read_b128 v[70:73], v186 offset:14336
	s_waitcnt lgkmcnt(8)
	v_mfma_scale_f32_32x32x64_f8f6f4 v[98:113], v[222:229], v[130:137], v[98:113], v194, v193 op_sel_hi:[0,0,0]
	v_mov_b32_e32 v0, v219
	s_nop 1
	v_permlane32_swap_b32_e32 v219, v0
	v_add_f32_e32 v219, v219, v0
	v_fma_f32 v209, v209, v218, v219
	v_max_f32_e32 v177, v114, v115
	v_max3_f32 v177, v177, v116, v117
	v_max3_f32 v177, v177, v118, v119
	v_max3_f32 v177, v177, v120, v121
	v_max3_f32 v177, v177, v122, v123
	v_max3_f32 v177, v177, v124, v125
	v_max3_f32 v177, v177, v126, v127
	v_max3_f32 v177, v177, v128, v129
	s_waitcnt lgkmcnt(6)
	v_mfma_scale_f32_32x32x64_f8f6f4 v[50:65], v[246:253], v[90:97], v[50:65], v194, v194 op_sel_hi:[0,0,0]
	s_waitcnt lgkmcnt(4)
	v_mfma_scale_f32_32x32x64_f8f6f4 v[34:49], v[246:253], v[82:89], v[34:49], v194, v194 op_sel_hi:[0,0,0]
	s_waitcnt vmcnt(0)
	ds_write_b128 v210, v[158:161]
	ds_write_b128 v211, v[162:165] offset:16384
	s_waitcnt lgkmcnt(0)
	s_barrier
	global_load_dwordx4 v[158:161], v176, s[18:19]
	global_load_dwordx4 v[162:165], v178, s[16:17]
	v_add_u32_e32 v176, 0x2000, v176
	v_add_u32_e32 v178, 0x20000, v178
	s_waitcnt lgkmcnt(2)
	v_mfma_scale_f32_32x32x64_f8f6f4 v[18:33], v[246:253], v[74:81], v[18:33], v194, v194 op_sel_hi:[0,0,0]
	s_waitcnt lgkmcnt(0)
	v_mfma_scale_f32_32x32x64_f8f6f4 v[2:17], v[246:253], v[66:73], v[2:17], v194, v194 op_sel_hi:[0,0,0]
	v_max_f32_e32 v0, v98, v99
	v_max3_f32 v0, v0, v100, v101
	v_max3_f32 v0, v0, v102, v103
	v_max3_f32 v0, v0, v104, v105
	v_max3_f32 v0, v0, v106, v107
	v_max3_f32 v0, v0, v108, v109
	v_max3_f32 v0, v0, v110, v111
	v_max3_f32 v0, v0, v112, v113
	v_max_f32_e32 v177, v177, v0
	v_mov_b32_e32 v0, v177
	v_mov_b32_e32 v221, 1.0
	s_nop 0
	v_permlane32_swap_b32_e32 v177, v0
	v_max_f32_e32 v177, v177, v0
	v_cmp_ge_f32_e32 vcc, s90, v177
	s_cmp_eq_u64 vcc, exec
	s_cbranch_scc0 .Lmla_s4_newmax
; __device__ __forceinline__ void finishSM9(f32x16& p0, f32x16& p1, float alpha, float& l_reg, v8i32& p8) {
; #pragma unroll
;   for (int r = 0; r < 16; ++r) { p0[r] = __builtin_amdgcn_exp2f(p0[r]); p1[r] = __builtin_amdgcn_exp2f(p1[r]); }
;   float ps = 0;
; #pragma unroll
;   for (int r = 0; r < 16; ++r) ps += p0[r];
; #pragma unroll
;   for (int r = 0; r < 16; ++r) ps += p1[r];
;   { auto rr = __builtin_amdgcn_permlane32_swap(__float_as_uint(ps), __float_as_uint(ps), false, false);
;     ps = __uint_as_float(rr[0]) + __uint_as_float(rr[1]); }
;   l_reg = l_reg * alpha + ps;
; #pragma unroll
;   for (int g = 0; g < 4; ++g) {
;     int w = __builtin_amdgcn_cvt_pk_fp8_f32(p0[4 * g], p0[4 * g + 1], 0, false); p8[g] = __builtin_amdgcn_cvt_pk_fp8_f32(p0[4 * g + 2], p0[4 * g + 3], w, true);
;     int u = __builtin_amdgcn_cvt_pk_fp8_f32(p1[4 * g], p1[4 * g + 1], 0, false); p8[4 + g] = __builtin_amdgcn_cvt_pk_fp8_f32(p1[4 * g + 2], p1[4 * g + 3], u, true); }
; }
; __device__ __forceinline__ void pv8(f32x16* o, const char* Vt, const v8i32 p8, int r32, int hi) {
;   const int sw = (r32 >> 2) & 3, a0 = r32 * 64 + (((hi * 2) ^ sw) << 4), a1 = r32 * 64 + (((hi * 2 + 1) ^ sw) << 4);
; #pragma unroll
;   for (int d0 = 0; d0 < 4; ++d0) {
;     const v8i32 vf = cat8(*reinterpret_cast<const v4i32*>(Vt + d0 * 2048 + a0), *reinterpret_cast<const v4i32*>(Vt + d0 * 2048 + a1));
;     o[d0] = __builtin_amdgcn_mfma_scale_f32_32x32x64_f8f6f4(p8, vf, o[d0], 0, 0, 0, 127, 0, 127); }
; }
; __device__ __forceinline__ void qkt9(f32x16& p0, f32x16& p1, const char* Kn, const char* Kr, const v8i32* qf, const float init, int r32, int hi) {
; #pragma unroll
;   for (int r = 0; r < 16; ++r) { p0[r] = init; p1[r] = init; }
; #pragma unroll
;   for (int s = 0; s < 2; ++s) { const int c0 = s * 4 + hi * 2;
;     const v8i32 a0 = cat8(*reinterpret_cast<const v4i32*>(Kn + KN8SW(r32, c0)), *reinterpret_cast<const v4i32*>(Kn + KN8SW(r32, c0 + 1)));
;     const v8i32 a1 = cat8(*reinterpret_cast<const v4i32*>(Kn + 4096 + KN8SW(r32, c0)), *reinterpret_cast<const v4i32*>(Kn + 4096 + KN8SW(r32, c0 + 1)));
;     p0 = __builtin_amdgcn_mfma_scale_f32_32x32x64_f8f6f4(a0, qf[s], p0, 0, 0, 0, 127, 0, 124);
;     p1 = __builtin_amdgcn_mfma_scale_f32_32x32x64_f8f6f4(a1, qf[s], p1, 0, 0, 0, 127, 0, 124); }
;   { const int c0 = hi * 2;
.Lmla_s4_cont:
	ds_read_b128 v[82:85], v215 offset:16384
	ds_read_b128 v[86:89], v216 offset:16384
	ds_read_b128 v[222:225], v215 offset:20480
	ds_read_b128 v[226:229], v216 offset:20480
	v_exp_f32_e32 v0, v114
	v_exp_f32_e32 v177, v115
	v_exp_f32_e32 v179, v116
	v_exp_f32_e32 v254, v117
	v_add_f32_e32 v219, v0, v177
	v_cvt_pk_fp8_f32 v246, v0, v177
	v_add_f32_e32 v219, v179, v219
	v_add_f32_e32 v219, v254, v219
	v_cvt_pk_fp8_f32 v246, v179, v254 op_sel:[0,0,1]
	s_waitcnt lgkmcnt(2)
	v_mfma_scale_f32_32x32x64_f8f6f4 v[82:97], v[82:89], v[146:153], v[230:245], v194, v193 op_sel_hi:[0,0,0]
	v_exp_f32_e32 v0, v118
	v_exp_f32_e32 v177, v119
	v_exp_f32_e32 v179, v120
	v_exp_f32_e32 v254, v121
	v_add_f32_e32 v219, v0, v219
	v_add_f32_e32 v219, v177, v219
	v_cvt_pk_fp8_f32 v247, v0, v177
	v_add_f32_e32 v219, v179, v219
	v_add_f32_e32 v219, v254, v219
	v_cvt_pk_fp8_f32 v247, v179, v254 op_sel:[0,0,1]
	ds_read_b128 v[114:117], v213 offset:16384
	ds_read_b128 v[118:121], v214 offset:16384
	s_waitcnt lgkmcnt(2)
	v_mfma_scale_f32_32x32x64_f8f6f4 v[66:81], v[222:229], v[146:153], v[230:245], v194, v193 op_sel_hi:[0,0,0]
	ds_read_b128 v[222:225], v213 offset:20480
	ds_read_b128 v[226:229], v214 offset:20480
	v_exp_f32_e32 v0, v122
	v_exp_f32_e32 v177, v123
	v_exp_f32_e32 v179, v124
	v_exp_f32_e32 v254, v125
	v_add_f32_e32 v219, v0, v219
	v_add_f32_e32 v219, v177, v219
	v_cvt_pk_fp8_f32 v248, v0, v177
	v_add_f32_e32 v219, v179, v219
	v_add_f32_e32 v219, v254, v219
	v_cvt_pk_fp8_f32 v248, v179, v254 op_sel:[0,0,1]
	v_exp_f32_e32 v0, v126
	v_exp_f32_e32 v177, v127
	v_exp_f32_e32 v179, v128
	v_exp_f32_e32 v254, v129
	v_add_f32_e32 v219, v0, v219
	v_add_f32_e32 v219, v177, v219
	v_cvt_pk_fp8_f32 v249, v0, v177
	v_add_f32_e32 v219, v179, v219
	v_add_f32_e32 v219, v254, v219
	v_cvt_pk_fp8_f32 v249, v179, v254 op_sel:[0,0,1]
	ds_read_b128 v[122:125], v185 offset:32768
	ds_read_b128 v[126:129], v186 offset:32768
	s_waitcnt lgkmcnt(4)
	v_mfma_scale_f32_32x32x64_f8f6f4 v[82:97], v[114:121], v[138:145], v[82:97], v194, v193 op_sel_hi:[0,0,0]
	v_exp_f32_e32 v0, v98
	v_exp_f32_e32 v177, v99
	v_exp_f32_e32 v179, v100
	v_exp_f32_e32 v254, v101
	v_add_f32_e32 v219, v0, v219
	v_add_f32_e32 v219, v177, v219
	v_cvt_pk_fp8_f32 v250, v0, v177
	v_add_f32_e32 v219, v179, v219
	v_add_f32_e32 v219, v254, v219
	v_cvt_pk_fp8_f32 v250, v179, v254 op_sel:[0,0,1]
	s_waitcnt lgkmcnt(2)
	v_mfma_scale_f32_32x32x64_f8f6f4 v[66:81], v[222:229], v[138:145], v[66:81], v194, v193 op_sel_hi:[0,0,0]
	ds_read_b128 v[222:225], v185 offset:34816
	ds_read_b128 v[226:229], v186 offset:34816
	v_exp_f32_e32 v0, v102
	v_exp_f32_e32 v177, v103
	v_exp_f32_e32 v179, v104
	v_exp_f32_e32 v254, v105
	v_add_f32_e32 v219, v0, v219
	v_add_f32_e32 v219, v177, v219
	v_cvt_pk_fp8_f32 v251, v0, v177
	v_add_f32_e32 v219, v179, v219
	v_add_f32_e32 v219, v254, v219
	v_cvt_pk_fp8_f32 v251, v179, v254 op_sel:[0,0,1]
	v_exp_f32_e32 v0, v106
	v_exp_f32_e32 v177, v107
	v_exp_f32_e32 v179, v108
	v_exp_f32_e32 v254, v109
	v_add_f32_e32 v219, v0, v219
	v_add_f32_e32 v219, v177, v219
	v_cvt_pk_fp8_f32 v252, v0, v177
	v_add_f32_e32 v219, v179, v219
	v_add_f32_e32 v219, v254, v219
	v_cvt_pk_fp8_f32 v252, v179, v254 op_sel:[0,0,1]
	s_waitcnt lgkmcnt(2)
	v_mfma_scale_f32_32x32x64_f8f6f4 v[82:97], v[122:129], v[130:137], v[82:97], v194, v193 op_sel_hi:[0,0,0]
	v_exp_f32_e32 v0, v110
	v_exp_f32_e32 v177, v111
	v_exp_f32_e32 v179, v112
	v_exp_f32_e32 v254, v113
	v_add_f32_e32 v219, v0, v219
	v_add_f32_e32 v219, v177, v219
	v_cvt_pk_fp8_f32 v253, v0, v177
	v_add_f32_e32 v219, v179, v219
	v_add_f32_e32 v219, v254, v219
	v_cvt_pk_fp8_f32 v253, v179, v254 op_sel:[0,0,1]
	ds_read_b128 v[122:125], v185 offset:43008
	ds_read_b128 v[126:129], v186 offset:43008
	ds_read_b128 v[114:117], v185 offset:45056
	ds_read_b128 v[118:121], v186 offset:45056
	ds_read_b128 v[106:109], v185 offset:47104
	ds_read_b128 v[110:113], v186 offset:47104
	ds_read_b128 v[98:101], v185 offset:49152
	ds_read_b128 v[102:105], v186 offset:49152
	s_waitcnt lgkmcnt(8)
	v_mfma_scale_f32_32x32x64_f8f6f4 v[66:81], v[222:229], v[130:137], v[66:81], v194, v193 op_sel_hi:[0,0,0]
	v_mov_b32_e32 v0, v219
	s_nop 1
	v_permlane32_swap_b32_e32 v219, v0
	v_add_f32_e32 v219, v219, v0
	v_fma_f32 v209, v209, v221, v219
	v_max_f32_e32 v177, v82, v83
	v_max3_f32 v177, v177, v84, v85
	v_max3_f32 v177, v177, v86, v87
	v_max3_f32 v177, v177, v88, v89
	v_max3_f32 v177, v177, v90, v91
	v_max3_f32 v177, v177, v92, v93
	v_max3_f32 v177, v177, v94, v95
	v_max3_f32 v177, v177, v96, v97
	s_waitcnt lgkmcnt(6)
	v_mfma_scale_f32_32x32x64_f8f6f4 v[50:65], v[246:253], v[122:129], v[50:65], v194, v194 op_sel_hi:[0,0,0]
	s_waitcnt lgkmcnt(4)
	v_mfma_scale_f32_32x32x64_f8f6f4 v[34:49], v[246:253], v[114:121], v[34:49], v194, v194 op_sel_hi:[0,0,0]
	s_waitcnt vmcnt(0)
	ds_write_b128 v210, v[158:161] offset:8192
	ds_write_b128 v211, v[162:165] offset:24576
	s_waitcnt lgkmcnt(0)
	s_barrier
	global_load_dwordx4 v[158:161], v176, s[18:19]
	global_load_dwordx4 v[162:165], v178, s[16:17]
	v_add_u32_e32 v176, 0x2000, v176
	v_add_u32_e32 v178, 0x20000, v178
	s_waitcnt lgkmcnt(2)
	v_mfma_scale_f32_32x32x64_f8f6f4 v[18:33], v[246:253], v[106:113], v[18:33], v194, v194 op_sel_hi:[0,0,0]
	s_waitcnt lgkmcnt(0)
	v_mfma_scale_f32_32x32x64_f8f6f4 v[2:17], v[246:253], v[98:105], v[2:17], v194, v194 op_sel_hi:[0,0,0]
	v_max_f32_e32 v0, v66, v67
	v_max3_f32 v0, v0, v68, v69
	v_max3_f32 v0, v0, v70, v71
	v_max3_f32 v0, v0, v72, v73
	v_max3_f32 v0, v0, v74, v75
	v_max3_f32 v0, v0, v76, v77
	v_max3_f32 v0, v0, v78, v79
	v_max3_f32 v0, v0, v80, v81
	v_max_f32_e32 v177, v177, v0
	v_mov_b32_e32 v0, v177
	v_mov_b32_e32 v218, 1.0
	s_nop 0
	v_permlane32_swap_b32_e32 v177, v0
	v_max_f32_e32 v177, v177, v0
	v_cmp_ge_f32_e32 vcc, s90, v177
	s_cmp_eq_u64 vcc, exec
	s_cbranch_scc0 .Lmla_s5_newmax
; __device__ __forceinline__ void finishSM9(f32x16& p0, f32x16& p1, float alpha, float& l_reg, v8i32& p8) {
; #pragma unroll
;   for (int r = 0; r < 16; ++r) { p0[r] = __builtin_amdgcn_exp2f(p0[r]); p1[r] = __builtin_amdgcn_exp2f(p1[r]); }
;   float ps = 0;
; #pragma unroll
;   for (int r = 0; r < 16; ++r) ps += p0[r];
; #pragma unroll
;   for (int r = 0; r < 16; ++r) ps += p1[r];
;   { auto rr = __builtin_amdgcn_permlane32_swap(__float_as_uint(ps), __float_as_uint(ps), false, false);
;     ps = __uint_as_float(rr[0]) + __uint_as_float(rr[1]); }
;   l_reg = l_reg * alpha + ps;
; #pragma unroll
;   for (int g = 0; g < 4; ++g) {
;     int w = __builtin_amdgcn_cvt_pk_fp8_f32(p0[4 * g], p0[4 * g + 1], 0, false); p8[g] = __builtin_amdgcn_cvt_pk_fp8_f32(p0[4 * g + 2], p0[4 * g + 3], w, true);
;     int u = __builtin_amdgcn_cvt_pk_fp8_f32(p1[4 * g], p1[4 * g + 1], 0, false); p8[4 + g] = __builtin_amdgcn_cvt_pk_fp8_f32(p1[4 * g + 2], p1[4 * g + 3], u, true); }
; }
; __device__ __forceinline__ void pv8(f32x16* o, const char* Vt, const v8i32 p8, int r32, int hi) {
;   const int sw = (r32 >> 2) & 3, a0 = r32 * 64 + (((hi * 2) ^ sw) << 4), a1 = r32 * 64 + (((hi * 2 + 1) ^ sw) << 4);
; #pragma unroll
;   for (int d0 = 0; d0 < 4; ++d0) {
;     const v8i32 vf = cat8(*reinterpret_cast<const v4i32*>(Vt + d0 * 2048 + a0), *reinterpret_cast<const v4i32*>(Vt + d0 * 2048 + a1));
;     o[d0] = __builtin_amdgcn_mfma_scale_f32_32x32x64_f8f6f4(p8, vf, o[d0], 0, 0, 0, 127, 0, 127); }
; }
; __device__ __forceinline__ void qkt9(f32x16& p0, f32x16& p1, const char* Kn, const char* Kr, const v8i32* qf, const float init, int r32, int hi) {
; #pragma unroll
;   for (int r = 0; r < 16; ++r) { p0[r] = init; p1[r] = init; }
; #pragma unroll
;   for (int s = 0; s < 2; ++s) { const int c0 = s * 4 + hi * 2;
;     const v8i32 a0 = cat8(*reinterpret_cast<const v4i32*>(Kn + KN8SW(r32, c0)), *reinterpret_cast<const v4i32*>(Kn + KN8SW(r32, c0 + 1)));
;     const v8i32 a1 = cat8(*reinterpret_cast<const v4i32*>(Kn + 4096 + KN8SW(r32, c0)), *reinterpret_cast<const v4i32*>(Kn + 4096 + KN8SW(r32, c0 + 1)));
;     p0 = __builtin_amdgcn_mfma_scale_f32_32x32x64_f8f6f4(a0, qf[s], p0, 0, 0, 0, 127, 0, 124);
;     p1 = __builtin_amdgcn_mfma_scale_f32_32x32x64_f8f6f4(a1, qf[s], p1, 0, 0, 0, 127, 0, 124); }
;   { const int c0 = hi * 2;
.Lmla_s5_cont:
	s_add_i32 s30, s30, 1
	s_cmpk_lt_u32 s30, 42
	s_cbranch_scc1 .Lmla_stag_loop
	ds_read_b128 v[114:117], v215 offset:24576
	ds_read_b128 v[118:121], v216 offset:24576
	ds_read_b128 v[222:225], v215 offset:28672
	ds_read_b128 v[226:229], v216 offset:28672
	v_exp_f32_e32 v0, v82
	v_exp_f32_e32 v177, v83
	v_exp_f32_e32 v179, v84
	v_exp_f32_e32 v254, v85
	v_add_f32_e32 v219, v0, v177
	v_cvt_pk_fp8_f32 v246, v0, v177
	v_add_f32_e32 v219, v179, v219
	v_add_f32_e32 v219, v254, v219
	v_cvt_pk_fp8_f32 v246, v179, v254 op_sel:[0,0,1]
	s_waitcnt lgkmcnt(2)
	v_mfma_scale_f32_32x32x64_f8f6f4 v[114:129], v[114:121], v[146:153], v[230:245], v194, v193 op_sel_hi:[0,0,0]
	v_exp_f32_e32 v0, v86
	v_exp_f32_e32 v177, v87
	v_exp_f32_e32 v179, v88
	v_exp_f32_e32 v254, v89
	v_add_f32_e32 v219, v0, v219
	v_add_f32_e32 v219, v177, v219
	v_cvt_pk_fp8_f32 v247, v0, v177
	v_add_f32_e32 v219, v179, v219
	v_add_f32_e32 v219, v254, v219
	v_cvt_pk_fp8_f32 v247, v179, v254 op_sel:[0,0,1]
	ds_read_b128 v[82:85], v213 offset:24576
	ds_read_b128 v[86:89], v214 offset:24576
	s_waitcnt lgkmcnt(2)
	v_mfma_scale_f32_32x32x64_f8f6f4 v[98:113], v[222:229], v[146:153], v[230:245], v194, v193 op_sel_hi:[0,0,0]
	ds_read_b128 v[222:225], v213 offset:28672
	ds_read_b128 v[226:229], v214 offset:28672
	v_exp_f32_e32 v0, v90
	v_exp_f32_e32 v177, v91
	v_exp_f32_e32 v179, v92
	v_exp_f32_e32 v254, v93
	v_add_f32_e32 v219, v0, v219
	v_add_f32_e32 v219, v177, v219
	v_cvt_pk_fp8_f32 v248, v0, v177
	v_add_f32_e32 v219, v179, v219
	v_add_f32_e32 v219, v254, v219
	v_cvt_pk_fp8_f32 v248, v179, v254 op_sel:[0,0,1]
	v_exp_f32_e32 v0, v94
	v_exp_f32_e32 v177, v95
	v_exp_f32_e32 v179, v96
	v_exp_f32_e32 v254, v97
	v_add_f32_e32 v219, v0, v219
	v_add_f32_e32 v219, v177, v219
	v_cvt_pk_fp8_f32 v249, v0, v177
	v_add_f32_e32 v219, v179, v219
	v_add_f32_e32 v219, v254, v219
	v_cvt_pk_fp8_f32 v249, v179, v254 op_sel:[0,0,1]
	ds_read_b128 v[90:93], v185 offset:36864
	ds_read_b128 v[94:97], v186 offset:36864
	s_waitcnt lgkmcnt(4)
	v_mfma_scale_f32_32x32x64_f8f6f4 v[114:129], v[82:89], v[138:145], v[114:129], v194, v193 op_sel_hi:[0,0,0]
	v_exp_f32_e32 v0, v66
	v_exp_f32_e32 v177, v67
	v_exp_f32_e32 v179, v68
	v_exp_f32_e32 v254, v69
	v_add_f32_e32 v219, v0, v219
	v_add_f32_e32 v219, v177, v219
	v_cvt_pk_fp8_f32 v250, v0, v177
	v_add_f32_e32 v219, v179, v219
	v_add_f32_e32 v219, v254, v219
	v_cvt_pk_fp8_f32 v250, v179, v254 op_sel:[0,0,1]
	s_waitcnt lgkmcnt(2)
	v_mfma_scale_f32_32x32x64_f8f6f4 v[98:113], v[222:229], v[138:145], v[98:113], v194, v193 op_sel_hi:[0,0,0]
	ds_read_b128 v[222:225], v185 offset:38912
	ds_read_b128 v[226:229], v186 offset:38912
	v_exp_f32_e32 v0, v70
	v_exp_f32_e32 v177, v71
	v_exp_f32_e32 v179, v72
	v_exp_f32_e32 v254, v73
	v_add_f32_e32 v219, v0, v219
	v_add_f32_e32 v219, v177, v219
	v_cvt_pk_fp8_f32 v251, v0, v177
	v_add_f32_e32 v219, v179, v219
	v_add_f32_e32 v219, v254, v219
	v_cvt_pk_fp8_f32 v251, v179, v254 op_sel:[0,0,1]
	v_exp_f32_e32 v0, v74
	v_exp_f32_e32 v177, v75
	v_exp_f32_e32 v179, v76
	v_exp_f32_e32 v254, v77
	v_add_f32_e32 v219, v0, v219
	v_add_f32_e32 v219, v177, v219
	v_cvt_pk_fp8_f32 v252, v0, v177
	v_add_f32_e32 v219, v179, v219
	v_add_f32_e32 v219, v254, v219
	v_cvt_pk_fp8_f32 v252, v179, v254 op_sel:[0,0,1]
	s_waitcnt lgkmcnt(2)
	v_mfma_scale_f32_32x32x64_f8f6f4 v[114:129], v[90:97], v[130:137], v[114:129], v194, v193 op_sel_hi:[0,0,0]
	v_exp_f32_e32 v0, v78
	v_exp_f32_e32 v177, v79
	v_exp_f32_e32 v179, v80
	v_exp_f32_e32 v254, v81
	v_add_f32_e32 v219, v0, v219
	v_add_f32_e32 v219, v177, v219
	v_cvt_pk_fp8_f32 v253, v0, v177
	v_add_f32_e32 v219, v179, v219
	v_add_f32_e32 v219, v254, v219
	v_cvt_pk_fp8_f32 v253, v179, v254 op_sel:[0,0,1]
	ds_read_b128 v[90:93], v185 offset:0
	ds_read_b128 v[94:97], v186 offset:0
	ds_read_b128 v[82:85], v185 offset:2048
	ds_read_b128 v[86:89], v186 offset:2048
	ds_read_b128 v[74:77], v185 offset:4096
	ds_read_b128 v[78:81], v186 offset:4096
	ds_read_b128 v[66:69], v185 offset:6144
	ds_read_b128 v[70:73], v186 offset:6144
	s_waitcnt lgkmcnt(8)
	v_mfma_scale_f32_32x32x64_f8f6f4 v[98:113], v[222:229], v[130:137], v[98:113], v194, v193 op_sel_hi:[0,0,0]
	v_mov_b32_e32 v0, v219
	s_nop 1
	v_permlane32_swap_b32_e32 v219, v0
	v_add_f32_e32 v219, v219, v0
	v_fma_f32 v209, v209, v218, v219
	v_max_f32_e32 v177, v114, v115
	v_max3_f32 v177, v177, v116, v117
	v_max3_f32 v177, v177, v118, v119
	v_max3_f32 v177, v177, v120, v121
	v_max3_f32 v177, v177, v122, v123
	v_max3_f32 v177, v177, v124, v125
	v_max3_f32 v177, v177, v126, v127
	v_max3_f32 v177, v177, v128, v129
	s_waitcnt lgkmcnt(6)
	v_mfma_scale_f32_32x32x64_f8f6f4 v[50:65], v[246:253], v[90:97], v[50:65], v194, v194 op_sel_hi:[0,0,0]
	s_waitcnt lgkmcnt(4)
	v_mfma_scale_f32_32x32x64_f8f6f4 v[34:49], v[246:253], v[82:89], v[34:49], v194, v194 op_sel_hi:[0,0,0]
	s_waitcnt vmcnt(0)
	ds_write_b128 v210, v[158:161] offset:43008
	ds_write_b128 v211, v[162:165] offset:51200
	s_waitcnt lgkmcnt(0)
	s_barrier
	global_load_dwordx4 v[158:161], v176, s[18:19]
	global_load_dwordx4 v[162:165], v178, s[16:17]
	v_add_u32_e32 v176, 0x2000, v176
	v_add_u32_e32 v178, 0x20000, v178
	s_waitcnt lgkmcnt(2)
	v_mfma_scale_f32_32x32x64_f8f6f4 v[18:33], v[246:253], v[74:81], v[18:33], v194, v194 op_sel_hi:[0,0,0]
	s_waitcnt lgkmcnt(0)
	v_mfma_scale_f32_32x32x64_f8f6f4 v[2:17], v[246:253], v[66:73], v[2:17], v194, v194 op_sel_hi:[0,0,0]
	v_max_f32_e32 v0, v98, v99
	v_max3_f32 v0, v0, v100, v101
	v_max3_f32 v0, v0, v102, v103
	v_max3_f32 v0, v0, v104, v105
	v_max3_f32 v0, v0, v106, v107
	v_max3_f32 v0, v0, v108, v109
	v_max3_f32 v0, v0, v110, v111
	v_max3_f32 v0, v0, v112, v113
	v_max_f32_e32 v177, v177, v0
	v_mov_b32_e32 v0, v177
	v_mov_b32_e32 v221, 1.0
	s_nop 0
	v_permlane32_swap_b32_e32 v177, v0
	v_max_f32_e32 v177, v177, v0
	v_cmp_ge_f32_e32 vcc, s90, v177
	s_cmp_eq_u64 vcc, exec
	s_cbranch_scc0 .Lmla_q0_newmax
; __device__ __forceinline__ void finishSM9(f32x16& p0, f32x16& p1, float alpha, float& l_reg, v8i32& p8) {
; #pragma unroll
;   for (int r = 0; r < 16; ++r) { p0[r] = __builtin_amdgcn_exp2f(p0[r]); p1[r] = __builtin_amdgcn_exp2f(p1[r]); }
;   float ps = 0;
; #pragma unroll
;   for (int r = 0; r < 16; ++r) ps += p0[r];
; #pragma unroll
;   for (int r = 0; r < 16; ++r) ps += p1[r];
;   { auto rr = __builtin_amdgcn_permlane32_swap(__float_as_uint(ps), __float_as_uint(ps), false, false);
;     ps = __uint_as_float(rr[0]) + __uint_as_float(rr[1]); }
;   l_reg = l_reg * alpha + ps;
; #pragma unroll
;   for (int g = 0; g < 4; ++g) {
;     int w = __builtin_amdgcn_cvt_pk_fp8_f32(p0[4 * g], p0[4 * g + 1], 0, false); p8[g] = __builtin_amdgcn_cvt_pk_fp8_f32(p0[4 * g + 2], p0[4 * g + 3], w, true);
;     int u = __builtin_amdgcn_cvt_pk_fp8_f32(p1[4 * g], p1[4 * g + 1], 0, false); p8[4 + g] = __builtin_amdgcn_cvt_pk_fp8_f32(p1[4 * g + 2], p1[4 * g + 3], u, true); }
; }
; __device__ __forceinline__ void pv8(f32x16* o, const char* Vt, const v8i32 p8, int r32, int hi) {
;   const int sw = (r32 >> 2) & 3, a0 = r32 * 64 + (((hi * 2) ^ sw) << 4), a1 = r32 * 64 + (((hi * 2 + 1) ^ sw) << 4);
; #pragma unroll
;   for (int d0 = 0; d0 < 4; ++d0) {
;     const v8i32 vf = cat8(*reinterpret_cast<const v4i32*>(Vt + d0 * 2048 + a0), *reinterpret_cast<const v4i32*>(Vt + d0 * 2048 + a1));
;     o[d0] = __builtin_amdgcn_mfma_scale_f32_32x32x64_f8f6f4(p8, vf, o[d0], 0, 0, 0, 127, 0, 127); }
; }
; __device__ __forceinline__ void qkt9(f32x16& p0, f32x16& p1, const char* Kn, const char* Kr, const v8i32* qf, const float init, int r32, int hi) {
; #pragma unroll
;   for (int r = 0; r < 16; ++r) { p0[r] = init; p1[r] = init; }
; #pragma unroll
;   for (int s = 0; s < 2; ++s) { const int c0 = s * 4 + hi * 2;
;     const v8i32 a0 = cat8(*reinterpret_cast<const v4i32*>(Kn + KN8SW(r32, c0)), *reinterpret_cast<const v4i32*>(Kn + KN8SW(r32, c0 + 1)));
;     const v8i32 a1 = cat8(*reinterpret_cast<const v4i32*>(Kn + 4096 + KN8SW(r32, c0)), *reinterpret_cast<const v4i32*>(Kn + 4096 + KN8SW(r32, c0 + 1)));
;     p0 = __builtin_amdgcn_mfma_scale_f32_32x32x64_f8f6f4(a0, qf[s], p0, 0, 0, 0, 127, 0, 124);
;     p1 = __builtin_amdgcn_mfma_scale_f32_32x32x64_f8f6f4(a1, qf[s], p1, 0, 0, 0, 127, 0, 124); }
;   { const int c0 = hi * 2;
.Lmla_q0_cont:
	ds_read_b128 v[82:85], v215 offset:51200
	ds_read_b128 v[86:89], v216 offset:51200
	ds_read_b128 v[222:225], v215 offset:55296
	ds_read_b128 v[226:229], v216 offset:55296
	v_exp_f32_e32 v0, v114
	v_exp_f32_e32 v177, v115
	v_exp_f32_e32 v179, v116
	v_exp_f32_e32 v254, v117
	v_add_f32_e32 v219, v0, v177
	v_cvt_pk_fp8_f32 v246, v0, v177
	v_add_f32_e32 v219, v179, v219
	v_add_f32_e32 v219, v254, v219
	v_cvt_pk_fp8_f32 v246, v179, v254 op_sel:[0,0,1]
	s_waitcnt lgkmcnt(2)
	v_mfma_scale_f32_32x32x64_f8f6f4 v[82:97], v[82:89], v[146:153], v[230:245], v194, v193 op_sel_hi:[0,0,0]
	v_exp_f32_e32 v0, v118
	v_exp_f32_e32 v177, v119
	v_exp_f32_e32 v179, v120
	v_exp_f32_e32 v254, v121
	v_add_f32_e32 v219, v0, v219
	v_add_f32_e32 v219, v177, v219
	v_cvt_pk_fp8_f32 v247, v0, v177
	v_add_f32_e32 v219, v179, v219
	v_add_f32_e32 v219, v254, v219
	v_cvt_pk_fp8_f32 v247, v179, v254 op_sel:[0,0,1]
	ds_read_b128 v[114:117], v213 offset:51200
	ds_read_b128 v[118:121], v214 offset:51200
	s_waitcnt lgkmcnt(2)
	v_mfma_scale_f32_32x32x64_f8f6f4 v[66:81], v[222:229], v[146:153], v[230:245], v194, v193 op_sel_hi:[0,0,0]
	ds_read_b128 v[222:225], v213 offset:55296
	ds_read_b128 v[226:229], v214 offset:55296
	v_exp_f32_e32 v0, v122
	v_exp_f32_e32 v177, v123
	v_exp_f32_e32 v179, v124
	v_exp_f32_e32 v254, v125
	v_add_f32_e32 v219, v0, v219
	v_add_f32_e32 v219, v177, v219
	v_cvt_pk_fp8_f32 v248, v0, v177
	v_add_f32_e32 v219, v179, v219
	v_add_f32_e32 v219, v254, v219
	v_cvt_pk_fp8_f32 v248, v179, v254 op_sel:[0,0,1]
	v_exp_f32_e32 v0, v126
	v_exp_f32_e32 v177, v127
	v_exp_f32_e32 v179, v128
	v_exp_f32_e32 v254, v129
	v_add_f32_e32 v219, v0, v219
	v_add_f32_e32 v219, v177, v219
	v_cvt_pk_fp8_f32 v249, v0, v177
	v_add_f32_e32 v219, v179, v219
	v_add_f32_e32 v219, v254, v219
	v_cvt_pk_fp8_f32 v249, v179, v254 op_sel:[0,0,1]
	ds_read_b128 v[122:125], v185 offset:59392
	ds_read_b128 v[126:129], v186 offset:59392
	s_waitcnt lgkmcnt(4)
	v_mfma_scale_f32_32x32x64_f8f6f4 v[82:97], v[114:121], v[138:145], v[82:97], v194, v193 op_sel_hi:[0,0,0]
	v_exp_f32_e32 v0, v98
	v_exp_f32_e32 v177, v99
	v_exp_f32_e32 v179, v100
	v_exp_f32_e32 v254, v101
	v_add_f32_e32 v219, v0, v219
	v_add_f32_e32 v219, v177, v219
	v_cvt_pk_fp8_f32 v250, v0, v177
	v_add_f32_e32 v219, v179, v219
	v_add_f32_e32 v219, v254, v219
	v_cvt_pk_fp8_f32 v250, v179, v254 op_sel:[0,0,1]
	s_waitcnt lgkmcnt(2)
	v_mfma_scale_f32_32x32x64_f8f6f4 v[66:81], v[222:229], v[138:145], v[66:81], v194, v193 op_sel_hi:[0,0,0]
	ds_read_b128 v[222:225], v185 offset:61440
	ds_read_b128 v[226:229], v186 offset:61440
	v_exp_f32_e32 v0, v102
	v_exp_f32_e32 v177, v103
	v_exp_f32_e32 v179, v104
	v_exp_f32_e32 v254, v105
	v_add_f32_e32 v219, v0, v219
	v_add_f32_e32 v219, v177, v219
	v_cvt_pk_fp8_f32 v251, v0, v177
	v_add_f32_e32 v219, v179, v219
	v_add_f32_e32 v219, v254, v219
	v_cvt_pk_fp8_f32 v251, v179, v254 op_sel:[0,0,1]
	v_exp_f32_e32 v0, v106
	v_exp_f32_e32 v177, v107
	v_exp_f32_e32 v179, v108
	v_exp_f32_e32 v254, v109
	v_add_f32_e32 v219, v0, v219
	v_add_f32_e32 v219, v177, v219
	v_cvt_pk_fp8_f32 v252, v0, v177
	v_add_f32_e32 v219, v179, v219
	v_add_f32_e32 v219, v254, v219
	v_cvt_pk_fp8_f32 v252, v179, v254 op_sel:[0,0,1]
	s_waitcnt lgkmcnt(2)
	v_mfma_scale_f32_32x32x64_f8f6f4 v[82:97], v[122:129], v[130:137], v[82:97], v194, v193 op_sel_hi:[0,0,0]
	v_exp_f32_e32 v0, v110
	v_exp_f32_e32 v177, v111
	v_exp_f32_e32 v179, v112
	v_exp_f32_e32 v254, v113
	v_add_f32_e32 v219, v0, v219
	v_add_f32_e32 v219, v177, v219
	v_cvt_pk_fp8_f32 v253, v0, v177
	v_add_f32_e32 v219, v179, v219
	v_add_f32_e32 v219, v254, v219
	v_cvt_pk_fp8_f32 v253, v179, v254 op_sel:[0,0,1]
	ds_read_b128 v[122:125], v185 offset:8192
	ds_read_b128 v[126:129], v186 offset:8192
	ds_read_b128 v[114:117], v185 offset:10240
	ds_read_b128 v[118:121], v186 offset:10240
	ds_read_b128 v[106:109], v185 offset:12288
	ds_read_b128 v[110:113], v186 offset:12288
	ds_read_b128 v[98:101], v185 offset:14336
	ds_read_b128 v[102:105], v186 offset:14336
	s_waitcnt lgkmcnt(8)
	v_mfma_scale_f32_32x32x64_f8f6f4 v[66:81], v[222:229], v[130:137], v[66:81], v194, v193 op_sel_hi:[0,0,0]
	v_mov_b32_e32 v0, v219
	s_nop 1
	v_permlane32_swap_b32_e32 v219, v0
	v_add_f32_e32 v219, v219, v0
	v_fma_f32 v209, v209, v221, v219
	v_max_f32_e32 v177, v82, v83
	v_max3_f32 v177, v177, v84, v85
	v_max3_f32 v177, v177, v86, v87
	v_max3_f32 v177, v177, v88, v89
	v_max3_f32 v177, v177, v90, v91
	v_max3_f32 v177, v177, v92, v93
	v_max3_f32 v177, v177, v94, v95
	v_max3_f32 v177, v177, v96, v97
	s_waitcnt lgkmcnt(6)
	v_mfma_scale_f32_32x32x64_f8f6f4 v[50:65], v[246:253], v[122:129], v[50:65], v194, v194 op_sel_hi:[0,0,0]
	s_waitcnt lgkmcnt(4)
	v_mfma_scale_f32_32x32x64_f8f6f4 v[34:49], v[246:253], v[114:121], v[34:49], v194, v194 op_sel_hi:[0,0,0]
	s_waitcnt vmcnt(0)
	ds_write_b128 v210, v[158:161]
	ds_write_b128 v211, v[162:165] offset:16384
	s_waitcnt lgkmcnt(0)
	s_barrier
	s_waitcnt lgkmcnt(2)
	v_mfma_scale_f32_32x32x64_f8f6f4 v[18:33], v[246:253], v[106:113], v[18:33], v194, v194 op_sel_hi:[0,0,0]
	s_waitcnt lgkmcnt(0)
	v_mfma_scale_f32_32x32x64_f8f6f4 v[2:17], v[246:253], v[98:105], v[2:17], v194, v194 op_sel_hi:[0,0,0]
	v_max_f32_e32 v0, v66, v67
	v_max3_f32 v0, v0, v68, v69
	v_max3_f32 v0, v0, v70, v71
	v_max3_f32 v0, v0, v72, v73
	v_max3_f32 v0, v0, v74, v75
	v_max3_f32 v0, v0, v76, v77
	v_max3_f32 v0, v0, v78, v79
	v_max3_f32 v0, v0, v80, v81
	v_max_f32_e32 v177, v177, v0
	v_mov_b32_e32 v0, v177
	v_mov_b32_e32 v218, 1.0
	s_nop 0
	v_permlane32_swap_b32_e32 v177, v0
	v_max_f32_e32 v177, v177, v0
	v_cmp_ge_f32_e32 vcc, s90, v177
	s_cmp_eq_u64 vcc, exec
	s_cbranch_scc0 .Lmla_q1_newmax

; __device__ __forceinline__ v8i32 cat8(v4i32 a, v4i32 b) { return (v8i32){a[0], a[1], a[2], a[3], b[0], b[1], b[2], b[3]}; }
; __device__ __forceinline__ void finishSM9(f32x16& p0, f32x16& p1, float alpha, float& l_reg, v8i32& p8) {
; #pragma unroll
;   for (int r = 0; r < 16; ++r) { p0[r] = __builtin_amdgcn_exp2f(p0[r]); p1[r] = __builtin_amdgcn_exp2f(p1[r]); }
;   float ps = 0;
; #pragma unroll
;   for (int r = 0; r < 16; ++r) ps += p0[r];
; #pragma unroll
;   for (int r = 0; r < 16; ++r) ps += p1[r];
;   { auto rr = __builtin_amdgcn_permlane32_swap(__float_as_uint(ps), __float_as_uint(ps), false, false);
;     ps = __uint_as_float(rr[0]) + __uint_as_float(rr[1]); }
;   l_reg = l_reg * alpha + ps;
; #pragma unroll
;   for (int g = 0; g < 4; ++g) {
;     int w = __builtin_amdgcn_cvt_pk_fp8_f32(p0[4 * g], p0[4 * g + 1], 0, false); p8[g] = __builtin_amdgcn_cvt_pk_fp8_f32(p0[4 * g + 2], p0[4 * g + 3], w, true);
;     int u = __builtin_amdgcn_cvt_pk_fp8_f32(p1[4 * g], p1[4 * g + 1], 0, false); p8[4 + g] = __builtin_amdgcn_cvt_pk_fp8_f32(p1[4 * g + 2], p1[4 * g + 3], u, true); }
; }
; __device__ __forceinline__ void pv8(f32x16* o, const char* Vt, const v8i32 p8, int r32, int hi) {
;   const int sw = (r32 >> 2) & 3, a0 = r32 * 64 + (((hi * 2) ^ sw) << 4), a1 = r32 * 64 + (((hi * 2 + 1) ^ sw) << 4);
; #pragma unroll
;   for (int d0 = 0; d0 < 4; ++d0) {
;     const v8i32 vf = cat8(*reinterpret_cast<const v4i32*>(Vt + d0 * 2048 + a0), *reinterpret_cast<const v4i32*>(Vt + d0 * 2048 + a1));
;     o[d0] = __builtin_amdgcn_mfma_scale_f32_32x32x64_f8f6f4(p8, vf, o[d0], 0, 0, 0, 127, 0, 127); }
; }
; __device__ __forceinline__ void attn_unit7(const unsigned char* __restrict__ Q8, int ldq, const unsigned char* __restrict__ Kn8, int ldk, const unsigned char* __restrict__ Kr8, ...
;     ...
;   if (hi == 0) li_l[r32] = l_reg; asm volatile("s_waitcnt lgkmcnt(0)" ::: "memory");
.LBB0_1348:
	v_exp_f32_e32 v139, v114
	v_exp_f32_e32 v141, v115
	v_exp_f32_e32 v114, v116
	v_exp_f32_e32 v116, v117
	v_exp_f32_e32 v140, v118
	v_add_f32_e32 v66, 0, v139
	v_exp_f32_e32 v142, v119
	v_add_f32_e32 v66, v141, v66
	v_exp_f32_e32 v119, v120
	v_add_f32_e32 v66, v114, v66
	v_exp_f32_e32 v138, v121
	v_add_f32_e32 v66, v116, v66
	v_exp_f32_e32 v120, v122
	v_add_f32_e32 v66, v140, v66
	v_exp_f32_e32 v122, v123
	v_add_f32_e32 v66, v142, v66
	v_exp_f32_e32 v133, v98
	v_exp_f32_e32 v98, v124
	v_add_f32_e32 v66, v119, v66
	v_exp_f32_e32 v115, v100
	v_exp_f32_e32 v100, v125
	v_add_f32_e32 v66, v138, v66
	v_exp_f32_e32 v121, v126
	v_add_f32_e32 v66, v120, v66
	v_exp_f32_e32 v118, v104
	v_exp_f32_e32 v104, v110
	v_exp_f32_e32 v110, v127
	v_add_f32_e32 v66, v122, v66
	v_exp_f32_e32 v135, v105
	v_exp_f32_e32 v105, v128
	v_add_f32_e32 v66, v98, v66
	v_exp_f32_e32 v117, v101
	v_exp_f32_e32 v101, v109
	v_exp_f32_e32 v109, v129
	v_add_f32_e32 v66, v100, v66
	v_add_f32_e32 v66, v121, v66
	v_exp_f32_e32 v136, v99
	v_add_f32_e32 v66, v110, v66
	v_add_f32_e32 v66, v105, v66
	v_add_f32_e32 v66, v109, v66
	v_exp_f32_e32 v134, v102
	v_add_f32_e32 v66, v133, v66
	v_exp_f32_e32 v137, v103
	v_add_f32_e32 v66, v136, v66
	v_add_f32_e32 v66, v115, v66
	v_add_f32_e32 v66, v117, v66
	v_exp_f32_e32 v103, v106
	v_add_f32_e32 v66, v134, v66
	v_exp_f32_e32 v107, v107
	v_add_f32_e32 v66, v137, v66
	v_exp_f32_e32 v99, v108
	v_add_f32_e32 v66, v118, v66
	v_add_f32_e32 v66, v135, v66
	v_add_f32_e32 v66, v103, v66
	v_exp_f32_e32 v108, v111
	v_add_f32_e32 v66, v107, v66
	v_exp_f32_e32 v102, v112
	v_add_f32_e32 v66, v99, v66
	v_add_f32_e32 v66, v101, v66
	v_add_f32_e32 v66, v104, v66
	v_add_f32_e32 v66, v108, v66
	v_add_f32_e32 v111, v102, v66
	ds_read_b128 v[90:93], v185
	ds_read_b128 v[82:85], v185 offset:2048
	ds_read_b128 v[94:97], v186
	ds_read_b128 v[86:89], v186 offset:2048
	ds_read_b128 v[74:77], v185 offset:4096
	ds_read_b128 v[66:69], v185 offset:6144
	ds_read_b128 v[78:81], v186 offset:4096
	ds_read_b128 v[70:73], v186 offset:6144
	v_exp_f32_e32 v106, v113
	s_nop 0
	v_add_f32_e32 v111, v106, v111
	v_mov_b32_e32 v112, v111
	s_nop 1
	v_permlane32_swap_b32_e32 v111, v112
	s_and_saveexec_b64 s[16:17], s[40:41]
	s_cbranch_execz .LBB0_1310
	v_add_f32_e32 v113, v130, v131
	v_fmac_f32_e32 v113, v209, v0
	v_add_f32_e32 v0, v111, v112
	v_fmac_f32_e32 v0, v113, v132
	ds_write_b32 v208, v0 offset:40960
	s_branch .LBB0_1310
